# EpiUp fast path: halo-dependent row tiles last (both halo sets loaded early), weights/row sums staged via LDS during last k-step
# speedup vs baseline: 1.0052x; 1.0052x over previous
;     __device__ __forceinline__ void operator()(const f32x4 (&acc)[2][2][4][2], const Unit& u, int wr, int wc, int fr, int fq) const {
;     ...
;             const int rowb = u.pm * 256 + ai * 128 + wr * 64;
;             const int blk = 4 * u.pm + 2 * ai + wr;
;             float rs[4];
; #pragma unroll
;             for (int m = 0; m < 4; ++m) rs[m] = rsqrtf(SS[rowb + 16 * m + fr] * (1.0f / D) + EPS);
; #pragma unroll
;             for (int n = 0; n < 2; ++n) {
;                 f32x4 cg[4];
; #pragma unroll
;                 for (int bj = 0; bj < 2; ++bj) {
;                     const int oc = (bj ? FF : 0) + 128 * u.pn + 32 * wc + 8 * fq + 4 * n;
;                     const int cgc = 256 * u.pn + 128 * bj + 32 * wc + 8 * fq + 4 * n;
;                     const f32x4 cw0 = *(const f32x4*)(convw + oc), cw1 = *(const f32x4*)(convw + FF2 + oc), cw2 = *(const f32x4*)(convw + 2 * FF2 + oc), cb = *(const f32x4*)(convb + oc);
;                     f32x4 v[4];
; #pragma unroll
;                     for (int m = 0; m < 4; ++m) v[m] = acc[ai][bj][m][n] * rs[m];
;                     f32x4 hv = (f32x4){0.f, 0.f, 0.f, 0.f};
.Lfe_begin:
	v_readlane_b32 s13, v236, 19
	s_lshl_b32 s77, s88, 8
	s_lshl_b32 s89, s12, 7
	s_lshl_b32 s75, s88, 2
	s_add_i32 s75, s75, s73
	s_add_i32 s77, s77, s13
	v_add_u32_e32 v246, s77, v153
	v_add_u32_e32 v247, s13, v153
	v_lshlrev_b32_e32 v247, 2, v247
	v_add_u32_e32 v247, 0x22000, v247
	ds_read2_b32 v[238:239], v247 offset0:0 offset1:16
	ds_read2_b32 v[240:241], v247 offset0:32 offset1:48
	ds_read2_b32 v[242:243], v247 offset0:128 offset1:144
	ds_read2_b32 v[244:245], v247 offset0:160 offset1:176
	v_lshlrev_b32_e32 v249, 2, v215
	v_add_u32_e32 v249, 0x21000, v249
	v_add_u32_e32 v248, s89, v215
	v_lshlrev_b32_e32 v237, 2, v248
	v_add_u32_e32 v250, 0x2c00, v237
	ds_read_b128 v[170:173], v249
	ds_read_b128 v[174:177], v249 offset:16
	ds_read_b128 v[178:181], v249 offset:512
	ds_read_b128 v[182:185], v249 offset:528
	ds_read_b128 v[186:189], v249 offset:1024
	ds_read_b128 v[190:193], v249 offset:1040
	ds_read_b128 v[194:197], v249 offset:1536
	ds_read_b128 v[198:201], v249 offset:1552
	v_mul_u32_u24_e32 v151, 0x1600, v246
	v_lshl_add_u32 v151, v248, 1, v151
	v_mov_b32_e32 v219, s64
	v_mov_b32_e32 v220, 0
	v_mov_b32_e32 v221, 0
	v_mov_b32_e32 v222, 0
	v_mov_b32_e32 v223, 0
	v_mov_b32_e32 v224, 0
	v_mov_b32_e32 v225, 0
	v_mov_b32_e32 v226, 0
	v_mov_b32_e32 v227, 0
	v_mov_b32_e32 v228, 0
	v_mov_b32_e32 v229, 0
	v_mov_b32_e32 v230, 0
	v_mov_b32_e32 v231, 0
	v_mov_b32_e32 v232, 0
	v_mov_b32_e32 v233, 0
	v_mov_b32_e32 v234, 0
	v_mov_b32_e32 v235, 0
	s_mul_i32 s56, s75, 0xb000
	s_lshl_b32 s57, s12, 10
	s_add_i32 s56, s56, s57
	v_mul_i32_i24_e32 v150, 0x5800, v216
	v_lshl_add_u32 v150, v215, 2, v150
	v_add_u32_e32 v150, s56, v150
	s_waitcnt lgkmcnt(8)
	v_fmamk_f32 v238, v238, 0x3a800000, v218
	v_fmamk_f32 v239, v239, 0x3a800000, v218
	v_fmamk_f32 v240, v240, 0x3a800000, v218
	v_fmamk_f32 v241, v241, 0x3a800000, v218
	v_fmamk_f32 v242, v242, 0x3a800000, v218
	v_fmamk_f32 v243, v243, 0x3a800000, v218
	v_fmamk_f32 v244, v244, 0x3a800000, v218
	v_fmamk_f32 v245, v245, 0x3a800000, v218
	v_rsq_f32_e32 v238, v238
	v_rsq_f32_e32 v239, v239
	v_rsq_f32_e32 v240, v240
	v_rsq_f32_e32 v241, v241
	v_rsq_f32_e32 v242, v242
	v_rsq_f32_e32 v243, v243
	v_rsq_f32_e32 v244, v244
	v_rsq_f32_e32 v245, v245
	ds_read_b128 v[202:205], v249 offset:2048
	ds_read_b128 v[206:209], v249 offset:2064
	ds_read_b128 v[210:213], v249 offset:2560
	ds_read_b128 v[128:131], v249 offset:2576
	ds_read_b128 v[132:135], v249 offset:3072
	ds_read_b128 v[136:139], v249 offset:3088
	ds_read_b128 v[140:143], v249 offset:3584
	ds_read_b128 v[144:147], v249 offset:3600
	v_pk_mul_f32 v[124:125], v[124:125], v[238:239] op_sel_hi:[1,0]
	v_pk_mul_f32 v[126:127], v[126:127], v[238:239] op_sel_hi:[1,0]
	v_pk_mul_f32 v[92:93], v[92:93], v[238:239] op_sel_hi:[1,0]
	v_pk_mul_f32 v[94:95], v[94:95], v[238:239] op_sel_hi:[1,0]
	v_pk_mul_f32 v[108:109], v[108:109], v[238:239] op_sel_hi:[1,0]
	v_pk_mul_f32 v[110:111], v[110:111], v[238:239] op_sel_hi:[1,0]
	v_pk_mul_f32 v[76:77], v[76:77], v[238:239] op_sel_hi:[1,0]
	v_pk_mul_f32 v[78:79], v[78:79], v[238:239] op_sel_hi:[1,0]
	v_pk_mul_f32 v[120:121], v[120:121], v[238:239] op_sel:[0,1] op_sel_hi:[1,1]
	v_pk_mul_f32 v[122:123], v[122:123], v[238:239] op_sel:[0,1] op_sel_hi:[1,1]
	v_pk_mul_f32 v[88:89], v[88:89], v[238:239] op_sel:[0,1] op_sel_hi:[1,1]
	v_pk_mul_f32 v[90:91], v[90:91], v[238:239] op_sel:[0,1] op_sel_hi:[1,1]
	v_pk_mul_f32 v[104:105], v[104:105], v[238:239] op_sel:[0,1] op_sel_hi:[1,1]
	v_pk_mul_f32 v[106:107], v[106:107], v[238:239] op_sel:[0,1] op_sel_hi:[1,1]
	v_pk_mul_f32 v[72:73], v[72:73], v[238:239] op_sel:[0,1] op_sel_hi:[1,1]
	v_pk_mul_f32 v[74:75], v[74:75], v[238:239] op_sel:[0,1] op_sel_hi:[1,1]
	v_pk_mul_f32 v[116:117], v[116:117], v[240:241] op_sel_hi:[1,0]
	v_pk_mul_f32 v[118:119], v[118:119], v[240:241] op_sel_hi:[1,0]
	v_pk_mul_f32 v[84:85], v[84:85], v[240:241] op_sel_hi:[1,0]
	v_pk_mul_f32 v[86:87], v[86:87], v[240:241] op_sel_hi:[1,0]
	v_pk_mul_f32 v[100:101], v[100:101], v[240:241] op_sel_hi:[1,0]
	v_pk_mul_f32 v[102:103], v[102:103], v[240:241] op_sel_hi:[1,0]
	v_pk_mul_f32 v[68:69], v[68:69], v[240:241] op_sel_hi:[1,0]
	v_pk_mul_f32 v[70:71], v[70:71], v[240:241] op_sel_hi:[1,0]
	v_pk_mul_f32 v[112:113], v[112:113], v[240:241] op_sel:[0,1] op_sel_hi:[1,1]
	v_pk_mul_f32 v[114:115], v[114:115], v[240:241] op_sel:[0,1] op_sel_hi:[1,1]
	v_pk_mul_f32 v[80:81], v[80:81], v[240:241] op_sel:[0,1] op_sel_hi:[1,1]
	v_pk_mul_f32 v[82:83], v[82:83], v[240:241] op_sel:[0,1] op_sel_hi:[1,1]
	v_pk_mul_f32 v[96:97], v[96:97], v[240:241] op_sel:[0,1] op_sel_hi:[1,1]
	v_pk_mul_f32 v[98:99], v[98:99], v[240:241] op_sel:[0,1] op_sel_hi:[1,1]
	v_pk_mul_f32 v[64:65], v[64:65], v[240:241] op_sel:[0,1] op_sel_hi:[1,1]
	v_pk_mul_f32 v[66:67], v[66:67], v[240:241] op_sel:[0,1] op_sel_hi:[1,1]
	v_pk_mul_f32 v[60:61], v[60:61], v[242:243] op_sel_hi:[1,0]
	v_pk_mul_f32 v[62:63], v[62:63], v[242:243] op_sel_hi:[1,0]
	v_pk_mul_f32 v[28:29], v[28:29], v[242:243] op_sel_hi:[1,0]
	v_pk_mul_f32 v[30:31], v[30:31], v[242:243] op_sel_hi:[1,0]
	v_pk_mul_f32 v[44:45], v[44:45], v[242:243] op_sel_hi:[1,0]
	v_pk_mul_f32 v[46:47], v[46:47], v[242:243] op_sel_hi:[1,0]
	v_pk_mul_f32 v[12:13], v[12:13], v[242:243] op_sel_hi:[1,0]
	v_pk_mul_f32 v[14:15], v[14:15], v[242:243] op_sel_hi:[1,0]
	v_pk_mul_f32 v[52:53], v[52:53], v[242:243] op_sel:[0,1] op_sel_hi:[1,1]
	v_pk_mul_f32 v[54:55], v[54:55], v[242:243] op_sel:[0,1] op_sel_hi:[1,1]
	v_pk_mul_f32 v[20:21], v[20:21], v[242:243] op_sel:[0,1] op_sel_hi:[1,1]
	v_pk_mul_f32 v[22:23], v[22:23], v[242:243] op_sel:[0,1] op_sel_hi:[1,1]
	v_pk_mul_f32 v[36:37], v[36:37], v[242:243] op_sel:[0,1] op_sel_hi:[1,1]
	v_pk_mul_f32 v[38:39], v[38:39], v[242:243] op_sel:[0,1] op_sel_hi:[1,1]
	v_pk_mul_f32 v[4:5], v[4:5], v[242:243] op_sel:[0,1] op_sel_hi:[1,1]
	v_pk_mul_f32 v[6:7], v[6:7], v[242:243] op_sel:[0,1] op_sel_hi:[1,1]
	v_pk_mul_f32 v[48:49], v[48:49], v[244:245] op_sel_hi:[1,0]
	v_pk_mul_f32 v[50:51], v[50:51], v[244:245] op_sel_hi:[1,0]
	v_pk_mul_f32 v[16:17], v[16:17], v[244:245] op_sel_hi:[1,0]
	v_pk_mul_f32 v[18:19], v[18:19], v[244:245] op_sel_hi:[1,0]
	v_pk_mul_f32 v[32:33], v[32:33], v[244:245] op_sel_hi:[1,0]
	v_pk_mul_f32 v[34:35], v[34:35], v[244:245] op_sel_hi:[1,0]
	v_pk_mul_f32 v[0:1], v[0:1], v[244:245] op_sel_hi:[1,0]
	v_pk_mul_f32 v[2:3], v[2:3], v[244:245] op_sel_hi:[1,0]
	v_pk_mul_f32 v[56:57], v[56:57], v[244:245] op_sel:[0,1] op_sel_hi:[1,1]
	v_pk_mul_f32 v[58:59], v[58:59], v[244:245] op_sel:[0,1] op_sel_hi:[1,1]
	v_pk_mul_f32 v[24:25], v[24:25], v[244:245] op_sel:[0,1] op_sel_hi:[1,1]
	v_pk_mul_f32 v[26:27], v[26:27], v[244:245] op_sel:[0,1] op_sel_hi:[1,1]
	v_pk_mul_f32 v[40:41], v[40:41], v[244:245] op_sel:[0,1] op_sel_hi:[1,1]
	v_pk_mul_f32 v[42:43], v[42:43], v[244:245] op_sel:[0,1] op_sel_hi:[1,1]
	v_pk_mul_f32 v[8:9], v[8:9], v[244:245] op_sel:[0,1] op_sel_hi:[1,1]
	v_pk_mul_f32 v[10:11], v[10:11], v[244:245] op_sel:[0,1] op_sel_hi:[1,1]
	s_waitcnt lgkmcnt(0)
; __device__ __forceinline__ unsigned cvt_pk_bf16(float lo, float hi) { unsigned r; asm volatile("v_cvt_pk_bf16_f32 %0, %1, %2" : "=v"(r) : "v"(lo), "v"(hi)); return r; }
;     __device__ __forceinline__ void operator()(const f32x4 (&acc)[2][2][4][2], const Unit& u, int wr, int wc, int fr, int fq) const {
;     ...
; #pragma unroll
;                     for (int m = 0; m < 4; ++m) {
;                         f32x4 cv;
;                         if (!samp) {
;                             const f32x4 prev = m ? v[m - 1] : hv;
; #pragma unroll
;                             for (int e = 0; e < 4; ++e) {
;                                 const int vi = __float_as_int(v[m][e]), pi = __float_as_int(prev[e]);
;                                 const int o1 = __builtin_amdgcn_mov_dpp(pi, 0x121, 0xf, 0xf, false);
;                                 const int o2 = __builtin_amdgcn_mov_dpp(pi, 0x122, 0xf, 0xf, false);
;                                 const float p1 = __int_as_float(__builtin_amdgcn_update_dpp(o1, vi, 0x111, 0xf, 0xf, false));
;                                 const float p2 = __int_as_float(__builtin_amdgcn_update_dpp(o2, vi, 0x112, 0xf, 0xf, false));
;                                 cv[e] = cb[e] + cw0[e] * p2 + cw1[e] * p1 + cw2[e] * v[m][e];
;                             }
;                         } else {
;                             const int ns = rowb + 16 * m + fr - MP;
;                             f32x4 s0 = (f32x4){0.f, 0.f, 0.f, 0.f}, s1 = s0;
;                             if (ns < NS) {
;                                 s0 = *(const f32x4*)(state + (size_t)(ns * 2 + 0) * FF2 + oc); s1 = *(const f32x4*)(state + (size_t)(ns * 2 + 1) * FF2 + oc);
;                                 *(f32x4*)(ncs + (size_t)(ns * 2 + 0) * FF2 + oc) = s1; *(f32x4*)(ncs + (size_t)(ns * 2 + 1) * FF2 + oc) = v[m];
;                             }
;                             cv = cb + cw0 * s0 + cw1 * s1 + cw2 * v[m];
;                         }
;                         if (bj == 0) cg[m] = gelu4(cv);
;                         else {
;                             const f32x4 r = cg[m] * cv;
;                             v2u w; w.x = cvt_pk_bf16(r[0], r[1]); w.y = cvt_pk_bf16(r[2], r[3]);
;                             *(v2u*)(ACT + (size_t)(rowb + 16 * m + fr) * FF + 128 * u.pn + 32 * wc + 8 * fq + 4 * n) = w;
;                         }
	v_mov_b32_dpp v220, v116 quad_perm:[0,1,2,3] row_mask:0xf bank_mask:0x8
	v_mov_b32_dpp v221, v117 quad_perm:[0,1,2,3] row_mask:0xf bank_mask:0x8
	v_mov_b32_dpp v222, v118 quad_perm:[0,1,2,3] row_mask:0xf bank_mask:0x8
	v_mov_b32_dpp v223, v119 quad_perm:[0,1,2,3] row_mask:0xf bank_mask:0x8
	v_pk_fma_f32 v[254:255], v[202:203], v[112:113], v[132:133]
	v_pk_fma_f32 v[148:149], v[204:205], v[114:115], v[134:135]
	v_fmac_f32_dpp v254, v112, v186 row_shr:1 row_mask:0xf bank_mask:0xf
	v_fmac_f32_dpp v255, v113, v187 row_shr:1 row_mask:0xf bank_mask:0xf
	v_fmac_f32_dpp v148, v114, v188 row_shr:1 row_mask:0xf bank_mask:0xf
	v_fmac_f32_dpp v149, v115, v189 row_shr:1 row_mask:0xf bank_mask:0xf
	v_fmac_f32_dpp v254, v112, v170 row_shr:2 row_mask:0xf bank_mask:0xf
	v_fmac_f32_dpp v255, v113, v171 row_shr:2 row_mask:0xf bank_mask:0xf
	v_fmac_f32_dpp v148, v114, v172 row_shr:2 row_mask:0xf bank_mask:0xf
	v_fmac_f32_dpp v149, v115, v173 row_shr:2 row_mask:0xf bank_mask:0xf
	v_fmac_f32_dpp v254, v220, v186 row_ror:1 row_mask:0xf bank_mask:0x1
	v_fmac_f32_dpp v255, v221, v187 row_ror:1 row_mask:0xf bank_mask:0x1
	v_fmac_f32_dpp v148, v222, v188 row_ror:1 row_mask:0xf bank_mask:0x1
	v_fmac_f32_dpp v149, v223, v189 row_ror:1 row_mask:0xf bank_mask:0x1
	v_fmac_f32_dpp v254, v220, v170 row_ror:2 row_mask:0xf bank_mask:0x1
	v_fmac_f32_dpp v255, v221, v171 row_ror:2 row_mask:0xf bank_mask:0x1
	v_fmac_f32_dpp v148, v222, v172 row_ror:2 row_mask:0xf bank_mask:0x1
	v_fmac_f32_dpp v149, v223, v173 row_ror:2 row_mask:0xf bank_mask:0x1
	v_fma_f32 v246, |v254|, s38, 1.0
	v_fma_f32 v247, |v255|, s38, 1.0
	v_fma_f32 v248, |v148|, s38, 1.0
	v_fma_f32 v249, |v149|, s38, 1.0
	v_mul_f32_e32 v250, v254, v254
	v_mul_f32_e32 v251, v255, v255
	v_mul_f32_e32 v252, v148, v148
	v_mul_f32_e32 v253, v149, v149
	v_rcp_f32_e32 v246, v246
	v_rcp_f32_e32 v247, v247
	v_rcp_f32_e32 v248, v248
	v_rcp_f32_e32 v249, v249
	v_mul_f32_e32 v250, s72, v250
	v_mul_f32_e32 v251, s72, v251
	v_mul_f32_e32 v252, s72, v252
	v_mul_f32_e32 v253, s72, v253
	v_exp_f32_e32 v250, v250
	v_exp_f32_e32 v251, v251
	v_exp_f32_e32 v252, v252
	v_exp_f32_e32 v253, v253
	v_fmamk_f32 v238, v246, 0x3f07dc22, v219
	v_fmamk_f32 v239, v247, 0x3f07dc22, v219
	v_fmamk_f32 v240, v248, 0x3f07dc22, v219
	v_fmamk_f32 v241, v249, 0x3f07dc22, v219
	v_fma_f32 v238, v246, v238, s66
	v_fma_f32 v239, v247, v239, s66
	v_fma_f32 v240, v248, v240, s66
	v_fma_f32 v241, v249, v241, s66
	v_fma_f32 v238, v246, v238, s68
	v_fma_f32 v239, v247, v239, s68
	v_fma_f32 v240, v248, v240, s68
	v_fma_f32 v241, v249, v241, s68
	v_fma_f32 v238, v246, v238, s70
	v_fma_f32 v239, v247, v239, s70
	v_fma_f32 v240, v248, v240, s70
	v_fma_f32 v241, v249, v241, s70
	v_mul_f32_e32 v238, v246, v238
	v_mul_f32_e32 v239, v247, v239
	v_mul_f32_e32 v240, v248, v240
	v_mul_f32_e32 v241, v249, v241
	v_mul_f32_e32 v238, v250, v238
	v_mul_f32_e32 v239, v251, v239
	v_mul_f32_e32 v240, v252, v240
	v_mul_f32_e32 v241, v253, v241
	v_max_f32_e32 v246, 0, v254
	v_max_f32_e32 v247, 0, v255
	v_max_f32_e32 v248, 0, v148
	v_max_f32_e32 v249, 0, v149
	v_fma_f32 v238, -|v254|, v238, v246
	v_fma_f32 v239, -|v255|, v239, v247
	v_fma_f32 v240, -|v148|, v240, v248
	v_fma_f32 v241, -|v149|, v241, v249
	v_mov_b32_dpp v220, v100 quad_perm:[0,1,2,3] row_mask:0xf bank_mask:0x8
	v_mov_b32_dpp v221, v101 quad_perm:[0,1,2,3] row_mask:0xf bank_mask:0x8
	v_mov_b32_dpp v222, v102 quad_perm:[0,1,2,3] row_mask:0xf bank_mask:0x8
	v_mov_b32_dpp v223, v103 quad_perm:[0,1,2,3] row_mask:0xf bank_mask:0x8
	v_pk_fma_f32 v[254:255], v[210:211], v[96:97], v[140:141]
	v_pk_fma_f32 v[148:149], v[212:213], v[98:99], v[142:143]
	v_fmac_f32_dpp v254, v96, v194 row_shr:1 row_mask:0xf bank_mask:0xf
	v_fmac_f32_dpp v255, v97, v195 row_shr:1 row_mask:0xf bank_mask:0xf
	v_fmac_f32_dpp v148, v98, v196 row_shr:1 row_mask:0xf bank_mask:0xf
	v_fmac_f32_dpp v149, v99, v197 row_shr:1 row_mask:0xf bank_mask:0xf
	v_fmac_f32_dpp v254, v96, v178 row_shr:2 row_mask:0xf bank_mask:0xf
	v_fmac_f32_dpp v255, v97, v179 row_shr:2 row_mask:0xf bank_mask:0xf
	v_fmac_f32_dpp v148, v98, v180 row_shr:2 row_mask:0xf bank_mask:0xf
	v_fmac_f32_dpp v149, v99, v181 row_shr:2 row_mask:0xf bank_mask:0xf
	v_fmac_f32_dpp v254, v220, v194 row_ror:1 row_mask:0xf bank_mask:0x1
	v_fmac_f32_dpp v255, v221, v195 row_ror:1 row_mask:0xf bank_mask:0x1
	v_fmac_f32_dpp v148, v222, v196 row_ror:1 row_mask:0xf bank_mask:0x1
	v_fmac_f32_dpp v149, v223, v197 row_ror:1 row_mask:0xf bank_mask:0x1
	v_fmac_f32_dpp v254, v220, v178 row_ror:2 row_mask:0xf bank_mask:0x1
	v_fmac_f32_dpp v255, v221, v179 row_ror:2 row_mask:0xf bank_mask:0x1
	v_fmac_f32_dpp v148, v222, v180 row_ror:2 row_mask:0xf bank_mask:0x1
	v_fmac_f32_dpp v149, v223, v181 row_ror:2 row_mask:0xf bank_mask:0x1
	v_pk_mul_f32 v[254:255], v[238:239], v[254:255]
	v_pk_mul_f32 v[148:149], v[240:241], v[148:149]
	v_cvt_pk_bf16_f32 v242, v254, v255
	v_cvt_pk_bf16_f32 v243, v148, v149
	v_mov_b32_dpp v220, v84 quad_perm:[0,1,2,3] row_mask:0xf bank_mask:0x8
	v_mov_b32_dpp v221, v85 quad_perm:[0,1,2,3] row_mask:0xf bank_mask:0x8
	v_mov_b32_dpp v222, v86 quad_perm:[0,1,2,3] row_mask:0xf bank_mask:0x8
	v_mov_b32_dpp v223, v87 quad_perm:[0,1,2,3] row_mask:0xf bank_mask:0x8
	v_pk_fma_f32 v[254:255], v[206:207], v[80:81], v[136:137]
	v_pk_fma_f32 v[148:149], v[208:209], v[82:83], v[138:139]
	v_fmac_f32_dpp v254, v80, v190 row_shr:1 row_mask:0xf bank_mask:0xf
	v_fmac_f32_dpp v255, v81, v191 row_shr:1 row_mask:0xf bank_mask:0xf
	v_fmac_f32_dpp v148, v82, v192 row_shr:1 row_mask:0xf bank_mask:0xf
	v_fmac_f32_dpp v149, v83, v193 row_shr:1 row_mask:0xf bank_mask:0xf
	v_fmac_f32_dpp v254, v80, v174 row_shr:2 row_mask:0xf bank_mask:0xf
; __device__ __forceinline__ unsigned cvt_pk_bf16(float lo, float hi) { unsigned r; asm volatile("v_cvt_pk_bf16_f32 %0, %1, %2" : "=v"(r) : "v"(lo), "v"(hi)); return r; }
;     __device__ __forceinline__ void operator()(const f32x4 (&acc)[2][2][4][2], const Unit& u, int wr, int wc, int fr, int fq) const {
;     ...
; #pragma unroll
;                     for (int m = 0; m < 4; ++m) {
;                         f32x4 cv;
;                         if (!samp) {
;                             const f32x4 prev = m ? v[m - 1] : hv;
; #pragma unroll
;                             for (int e = 0; e < 4; ++e) {
;                                 const int vi = __float_as_int(v[m][e]), pi = __float_as_int(prev[e]);
;                                 const int o1 = __builtin_amdgcn_mov_dpp(pi, 0x121, 0xf, 0xf, false);
;                                 const int o2 = __builtin_amdgcn_mov_dpp(pi, 0x122, 0xf, 0xf, false);
;                                 const float p1 = __int_as_float(__builtin_amdgcn_update_dpp(o1, vi, 0x111, 0xf, 0xf, false));
;                                 const float p2 = __int_as_float(__builtin_amdgcn_update_dpp(o2, vi, 0x112, 0xf, 0xf, false));
;                                 cv[e] = cb[e] + cw0[e] * p2 + cw1[e] * p1 + cw2[e] * v[m][e];
;                             }
;                         } else {
;                             const int ns = rowb + 16 * m + fr - MP;
;                             f32x4 s0 = (f32x4){0.f, 0.f, 0.f, 0.f}, s1 = s0;
;                             if (ns < NS) {
;                                 s0 = *(const f32x4*)(state + (size_t)(ns * 2 + 0) * FF2 + oc); s1 = *(const f32x4*)(state + (size_t)(ns * 2 + 1) * FF2 + oc);
;                                 *(f32x4*)(ncs + (size_t)(ns * 2 + 0) * FF2 + oc) = s1; *(f32x4*)(ncs + (size_t)(ns * 2 + 1) * FF2 + oc) = v[m];
;                             }
;                             cv = cb + cw0 * s0 + cw1 * s1 + cw2 * v[m];
;                         }
;                         if (bj == 0) cg[m] = gelu4(cv);
;                         else {
;                             const f32x4 r = cg[m] * cv;
;                             v2u w; w.x = cvt_pk_bf16(r[0], r[1]); w.y = cvt_pk_bf16(r[2], r[3]);
;                             *(v2u*)(ACT + (size_t)(rowb + 16 * m + fr) * FF + 128 * u.pn + 32 * wc + 8 * fq + 4 * n) = w;
;                         }
	v_fmac_f32_dpp v255, v81, v175 row_shr:2 row_mask:0xf bank_mask:0xf
	v_fmac_f32_dpp v148, v82, v176 row_shr:2 row_mask:0xf bank_mask:0xf
	v_fmac_f32_dpp v149, v83, v177 row_shr:2 row_mask:0xf bank_mask:0xf
	v_fmac_f32_dpp v254, v220, v190 row_ror:1 row_mask:0xf bank_mask:0x1
	v_fmac_f32_dpp v255, v221, v191 row_ror:1 row_mask:0xf bank_mask:0x1
	v_fmac_f32_dpp v148, v222, v192 row_ror:1 row_mask:0xf bank_mask:0x1
	v_fmac_f32_dpp v149, v223, v193 row_ror:1 row_mask:0xf bank_mask:0x1
	v_fmac_f32_dpp v254, v220, v174 row_ror:2 row_mask:0xf bank_mask:0x1
	v_fmac_f32_dpp v255, v221, v175 row_ror:2 row_mask:0xf bank_mask:0x1
	v_fmac_f32_dpp v148, v222, v176 row_ror:2 row_mask:0xf bank_mask:0x1
	v_fmac_f32_dpp v149, v223, v177 row_ror:2 row_mask:0xf bank_mask:0x1
	v_fma_f32 v246, |v254|, s38, 1.0
	v_fma_f32 v247, |v255|, s38, 1.0
	v_fma_f32 v248, |v148|, s38, 1.0
	v_fma_f32 v249, |v149|, s38, 1.0
	v_mul_f32_e32 v250, v254, v254
	v_mul_f32_e32 v251, v255, v255
	v_mul_f32_e32 v252, v148, v148
	v_mul_f32_e32 v253, v149, v149
	v_rcp_f32_e32 v246, v246
	v_rcp_f32_e32 v247, v247
	v_rcp_f32_e32 v248, v248
	v_rcp_f32_e32 v249, v249
	v_mul_f32_e32 v250, s72, v250
	v_mul_f32_e32 v251, s72, v251
	v_mul_f32_e32 v252, s72, v252
	v_mul_f32_e32 v253, s72, v253
	v_exp_f32_e32 v250, v250
	v_exp_f32_e32 v251, v251
	v_exp_f32_e32 v252, v252
	v_exp_f32_e32 v253, v253
	v_fmamk_f32 v238, v246, 0x3f07dc22, v219
	v_fmamk_f32 v239, v247, 0x3f07dc22, v219
	v_fmamk_f32 v240, v248, 0x3f07dc22, v219
	v_fmamk_f32 v241, v249, 0x3f07dc22, v219
	v_fma_f32 v238, v246, v238, s66
	v_fma_f32 v239, v247, v239, s66
	v_fma_f32 v240, v248, v240, s66
	v_fma_f32 v241, v249, v241, s66
	v_fma_f32 v238, v246, v238, s68
	v_fma_f32 v239, v247, v239, s68
	v_fma_f32 v240, v248, v240, s68
	v_fma_f32 v241, v249, v241, s68
	v_fma_f32 v238, v246, v238, s70
	v_fma_f32 v239, v247, v239, s70
	v_fma_f32 v240, v248, v240, s70
	v_fma_f32 v241, v249, v241, s70
	v_mul_f32_e32 v238, v246, v238
	v_mul_f32_e32 v239, v247, v239
	v_mul_f32_e32 v240, v248, v240
	v_mul_f32_e32 v241, v249, v241
	v_mul_f32_e32 v238, v250, v238
	v_mul_f32_e32 v239, v251, v239
	v_mul_f32_e32 v240, v252, v240
	v_mul_f32_e32 v241, v253, v241
	v_max_f32_e32 v246, 0, v254
	v_max_f32_e32 v247, 0, v255
	v_max_f32_e32 v248, 0, v148
	v_max_f32_e32 v249, 0, v149
	v_fma_f32 v238, -|v254|, v238, v246
	v_fma_f32 v239, -|v255|, v239, v247
	v_fma_f32 v240, -|v148|, v240, v248
	v_fma_f32 v241, -|v149|, v241, v249
	v_mov_b32_dpp v220, v68 quad_perm:[0,1,2,3] row_mask:0xf bank_mask:0x8
	v_mov_b32_dpp v221, v69 quad_perm:[0,1,2,3] row_mask:0xf bank_mask:0x8
	v_mov_b32_dpp v222, v70 quad_perm:[0,1,2,3] row_mask:0xf bank_mask:0x8
	v_mov_b32_dpp v223, v71 quad_perm:[0,1,2,3] row_mask:0xf bank_mask:0x8
	v_pk_fma_f32 v[254:255], v[128:129], v[64:65], v[144:145]
	v_pk_fma_f32 v[148:149], v[130:131], v[66:67], v[146:147]
	v_fmac_f32_dpp v254, v64, v198 row_shr:1 row_mask:0xf bank_mask:0xf
	v_fmac_f32_dpp v255, v65, v199 row_shr:1 row_mask:0xf bank_mask:0xf
	v_fmac_f32_dpp v148, v66, v200 row_shr:1 row_mask:0xf bank_mask:0xf
	v_fmac_f32_dpp v149, v67, v201 row_shr:1 row_mask:0xf bank_mask:0xf
	v_fmac_f32_dpp v254, v64, v182 row_shr:2 row_mask:0xf bank_mask:0xf
	v_fmac_f32_dpp v255, v65, v183 row_shr:2 row_mask:0xf bank_mask:0xf
	v_fmac_f32_dpp v148, v66, v184 row_shr:2 row_mask:0xf bank_mask:0xf
	v_fmac_f32_dpp v149, v67, v185 row_shr:2 row_mask:0xf bank_mask:0xf
	v_fmac_f32_dpp v254, v220, v198 row_ror:1 row_mask:0xf bank_mask:0x1
	v_fmac_f32_dpp v255, v221, v199 row_ror:1 row_mask:0xf bank_mask:0x1
	v_fmac_f32_dpp v148, v222, v200 row_ror:1 row_mask:0xf bank_mask:0x1
	v_fmac_f32_dpp v149, v223, v201 row_ror:1 row_mask:0xf bank_mask:0x1
	v_fmac_f32_dpp v254, v220, v182 row_ror:2 row_mask:0xf bank_mask:0x1
	v_fmac_f32_dpp v255, v221, v183 row_ror:2 row_mask:0xf bank_mask:0x1
	v_fmac_f32_dpp v148, v222, v184 row_ror:2 row_mask:0xf bank_mask:0x1
	v_fmac_f32_dpp v149, v223, v185 row_ror:2 row_mask:0xf bank_mask:0x1
	v_pk_mul_f32 v[254:255], v[238:239], v[254:255]
	v_pk_mul_f32 v[148:149], v[240:241], v[148:149]
	v_cvt_pk_bf16_f32 v244, v254, v255
	v_cvt_pk_bf16_f32 v245, v148, v149
	s_add_u32 s56, s46, 0x42000
	s_addc_u32 s57, s47, 0
	global_store_dwordx4 v151, v[242:245], s[56:57]
	v_mov_b32_e32 v112, 0
	v_mov_b32_e32 v113, 0
	v_mov_b32_e32 v114, 0
	v_mov_b32_e32 v115, 0
	v_mov_b32_dpp v112, v120 quad_perm:[0,1,2,3] row_mask:0xf bank_mask:0x8
	v_mov_b32_dpp v113, v121 quad_perm:[0,1,2,3] row_mask:0xf bank_mask:0x8
	v_mov_b32_dpp v114, v122 quad_perm:[0,1,2,3] row_mask:0xf bank_mask:0x8
	v_mov_b32_dpp v115, v123 quad_perm:[0,1,2,3] row_mask:0xf bank_mask:0x8
	v_pk_fma_f32 v[254:255], v[202:203], v[116:117], v[132:133]
	v_pk_fma_f32 v[148:149], v[204:205], v[118:119], v[134:135]
	v_fmac_f32_dpp v254, v116, v186 row_shr:1 row_mask:0xf bank_mask:0xf
	v_fmac_f32_dpp v255, v117, v187 row_shr:1 row_mask:0xf bank_mask:0xf
	v_fmac_f32_dpp v148, v118, v188 row_shr:1 row_mask:0xf bank_mask:0xf
	v_fmac_f32_dpp v149, v119, v189 row_shr:1 row_mask:0xf bank_mask:0xf
	v_fmac_f32_dpp v254, v116, v170 row_shr:2 row_mask:0xf bank_mask:0xf
	v_fmac_f32_dpp v255, v117, v171 row_shr:2 row_mask:0xf bank_mask:0xf
	v_fmac_f32_dpp v148, v118, v172 row_shr:2 row_mask:0xf bank_mask:0xf
	v_fmac_f32_dpp v149, v119, v173 row_shr:2 row_mask:0xf bank_mask:0xf
	v_fmac_f32_dpp v254, v112, v186 row_ror:1 row_mask:0xf bank_mask:0x1
	v_fmac_f32_dpp v255, v113, v187 row_ror:1 row_mask:0xf bank_mask:0x1
	v_fmac_f32_dpp v148, v114, v188 row_ror:1 row_mask:0xf bank_mask:0x1
	v_fmac_f32_dpp v149, v115, v189 row_ror:1 row_mask:0xf bank_mask:0x1
	v_fmac_f32_dpp v254, v112, v170 row_ror:2 row_mask:0xf bank_mask:0x1
; __device__ __forceinline__ unsigned cvt_pk_bf16(float lo, float hi) { unsigned r; asm volatile("v_cvt_pk_bf16_f32 %0, %1, %2" : "=v"(r) : "v"(lo), "v"(hi)); return r; }
;     __device__ __forceinline__ void operator()(const f32x4 (&acc)[2][2][4][2], const Unit& u, int wr, int wc, int fr, int fq) const {
;     ...
; #pragma unroll
;                     for (int m = 0; m < 4; ++m) {
;                         f32x4 cv;
;                         if (!samp) {
;                             const f32x4 prev = m ? v[m - 1] : hv;
; #pragma unroll
;                             for (int e = 0; e < 4; ++e) {
;                                 const int vi = __float_as_int(v[m][e]), pi = __float_as_int(prev[e]);
;                                 const int o1 = __builtin_amdgcn_mov_dpp(pi, 0x121, 0xf, 0xf, false);
;                                 const int o2 = __builtin_amdgcn_mov_dpp(pi, 0x122, 0xf, 0xf, false);
;                                 const float p1 = __int_as_float(__builtin_amdgcn_update_dpp(o1, vi, 0x111, 0xf, 0xf, false));
;                                 const float p2 = __int_as_float(__builtin_amdgcn_update_dpp(o2, vi, 0x112, 0xf, 0xf, false));
;                                 cv[e] = cb[e] + cw0[e] * p2 + cw1[e] * p1 + cw2[e] * v[m][e];
;                             }
;                         } else {
;                             const int ns = rowb + 16 * m + fr - MP;
;                             f32x4 s0 = (f32x4){0.f, 0.f, 0.f, 0.f}, s1 = s0;
;                             if (ns < NS) {
;                                 s0 = *(const f32x4*)(state + (size_t)(ns * 2 + 0) * FF2 + oc); s1 = *(const f32x4*)(state + (size_t)(ns * 2 + 1) * FF2 + oc);
;                                 *(f32x4*)(ncs + (size_t)(ns * 2 + 0) * FF2 + oc) = s1; *(f32x4*)(ncs + (size_t)(ns * 2 + 1) * FF2 + oc) = v[m];
;                             }
;                             cv = cb + cw0 * s0 + cw1 * s1 + cw2 * v[m];
;                         }
;                         if (bj == 0) cg[m] = gelu4(cv);
;                         else {
;                             const f32x4 r = cg[m] * cv;
;                             v2u w; w.x = cvt_pk_bf16(r[0], r[1]); w.y = cvt_pk_bf16(r[2], r[3]);
;                             *(v2u*)(ACT + (size_t)(rowb + 16 * m + fr) * FF + 128 * u.pn + 32 * wc + 8 * fq + 4 * n) = w;
;                         }
	v_fmac_f32_dpp v255, v113, v171 row_ror:2 row_mask:0xf bank_mask:0x1
	v_fmac_f32_dpp v148, v114, v172 row_ror:2 row_mask:0xf bank_mask:0x1
	v_fmac_f32_dpp v149, v115, v173 row_ror:2 row_mask:0xf bank_mask:0x1
	v_fma_f32 v246, |v254|, s38, 1.0
	v_fma_f32 v247, |v255|, s38, 1.0
	v_fma_f32 v248, |v148|, s38, 1.0
	v_fma_f32 v249, |v149|, s38, 1.0
	v_mul_f32_e32 v250, v254, v254
	v_mul_f32_e32 v251, v255, v255
	v_mul_f32_e32 v252, v148, v148
	v_mul_f32_e32 v253, v149, v149
	v_rcp_f32_e32 v246, v246
	v_rcp_f32_e32 v247, v247
	v_rcp_f32_e32 v248, v248
	v_rcp_f32_e32 v249, v249
	v_mul_f32_e32 v250, s72, v250
	v_mul_f32_e32 v251, s72, v251
	v_mul_f32_e32 v252, s72, v252
	v_mul_f32_e32 v253, s72, v253
	v_exp_f32_e32 v250, v250
	v_exp_f32_e32 v251, v251
	v_exp_f32_e32 v252, v252
	v_exp_f32_e32 v253, v253
	v_fmamk_f32 v238, v246, 0x3f07dc22, v219
	v_fmamk_f32 v239, v247, 0x3f07dc22, v219
	v_fmamk_f32 v240, v248, 0x3f07dc22, v219
	v_fmamk_f32 v241, v249, 0x3f07dc22, v219
	v_fma_f32 v238, v246, v238, s66
	v_fma_f32 v239, v247, v239, s66
	v_fma_f32 v240, v248, v240, s66
	v_fma_f32 v241, v249, v241, s66
	v_fma_f32 v238, v246, v238, s68
	v_fma_f32 v239, v247, v239, s68
	v_fma_f32 v240, v248, v240, s68
	v_fma_f32 v241, v249, v241, s68
	v_fma_f32 v238, v246, v238, s70
	v_fma_f32 v239, v247, v239, s70
	v_fma_f32 v240, v248, v240, s70
	v_fma_f32 v241, v249, v241, s70
	v_mul_f32_e32 v238, v246, v238
	v_mul_f32_e32 v239, v247, v239
	v_mul_f32_e32 v240, v248, v240
	v_mul_f32_e32 v241, v249, v241
	v_mul_f32_e32 v238, v250, v238
	v_mul_f32_e32 v239, v251, v239
	v_mul_f32_e32 v240, v252, v240
	v_mul_f32_e32 v241, v253, v241
	v_max_f32_e32 v246, 0, v254
	v_max_f32_e32 v247, 0, v255
	v_max_f32_e32 v248, 0, v148
	v_max_f32_e32 v249, 0, v149
	v_fma_f32 v238, -|v254|, v238, v246
	v_fma_f32 v239, -|v255|, v239, v247
	v_fma_f32 v240, -|v148|, v240, v248
	v_fma_f32 v241, -|v149|, v241, v249
	v_mov_b32_dpp v112, v104 quad_perm:[0,1,2,3] row_mask:0xf bank_mask:0x8
	v_mov_b32_dpp v113, v105 quad_perm:[0,1,2,3] row_mask:0xf bank_mask:0x8
	v_mov_b32_dpp v114, v106 quad_perm:[0,1,2,3] row_mask:0xf bank_mask:0x8
	v_mov_b32_dpp v115, v107 quad_perm:[0,1,2,3] row_mask:0xf bank_mask:0x8
	v_pk_fma_f32 v[254:255], v[210:211], v[100:101], v[140:141]
	v_pk_fma_f32 v[148:149], v[212:213], v[102:103], v[142:143]
	v_fmac_f32_dpp v254, v100, v194 row_shr:1 row_mask:0xf bank_mask:0xf
	v_fmac_f32_dpp v255, v101, v195 row_shr:1 row_mask:0xf bank_mask:0xf
	v_fmac_f32_dpp v148, v102, v196 row_shr:1 row_mask:0xf bank_mask:0xf
	v_fmac_f32_dpp v149, v103, v197 row_shr:1 row_mask:0xf bank_mask:0xf
	v_fmac_f32_dpp v254, v100, v178 row_shr:2 row_mask:0xf bank_mask:0xf
	v_fmac_f32_dpp v255, v101, v179 row_shr:2 row_mask:0xf bank_mask:0xf
	v_fmac_f32_dpp v148, v102, v180 row_shr:2 row_mask:0xf bank_mask:0xf
	v_fmac_f32_dpp v149, v103, v181 row_shr:2 row_mask:0xf bank_mask:0xf
	v_fmac_f32_dpp v254, v112, v194 row_ror:1 row_mask:0xf bank_mask:0x1
	v_fmac_f32_dpp v255, v113, v195 row_ror:1 row_mask:0xf bank_mask:0x1
	v_fmac_f32_dpp v148, v114, v196 row_ror:1 row_mask:0xf bank_mask:0x1
	v_fmac_f32_dpp v149, v115, v197 row_ror:1 row_mask:0xf bank_mask:0x1
	v_fmac_f32_dpp v254, v112, v178 row_ror:2 row_mask:0xf bank_mask:0x1
	v_fmac_f32_dpp v255, v113, v179 row_ror:2 row_mask:0xf bank_mask:0x1
	v_fmac_f32_dpp v148, v114, v180 row_ror:2 row_mask:0xf bank_mask:0x1
	v_fmac_f32_dpp v149, v115, v181 row_ror:2 row_mask:0xf bank_mask:0x1
	v_pk_mul_f32 v[254:255], v[238:239], v[254:255]
	v_pk_mul_f32 v[148:149], v[240:241], v[148:149]
	v_cvt_pk_bf16_f32 v242, v254, v255
	v_cvt_pk_bf16_f32 v243, v148, v149
	v_mov_b32_dpp v112, v88 quad_perm:[0,1,2,3] row_mask:0xf bank_mask:0x8
	v_mov_b32_dpp v113, v89 quad_perm:[0,1,2,3] row_mask:0xf bank_mask:0x8
	v_mov_b32_dpp v114, v90 quad_perm:[0,1,2,3] row_mask:0xf bank_mask:0x8
	v_mov_b32_dpp v115, v91 quad_perm:[0,1,2,3] row_mask:0xf bank_mask:0x8
	v_pk_fma_f32 v[254:255], v[206:207], v[84:85], v[136:137]
	v_pk_fma_f32 v[148:149], v[208:209], v[86:87], v[138:139]
	v_fmac_f32_dpp v254, v84, v190 row_shr:1 row_mask:0xf bank_mask:0xf
	v_fmac_f32_dpp v255, v85, v191 row_shr:1 row_mask:0xf bank_mask:0xf
	v_fmac_f32_dpp v148, v86, v192 row_shr:1 row_mask:0xf bank_mask:0xf
	v_fmac_f32_dpp v149, v87, v193 row_shr:1 row_mask:0xf bank_mask:0xf
	v_fmac_f32_dpp v254, v84, v174 row_shr:2 row_mask:0xf bank_mask:0xf
	v_fmac_f32_dpp v255, v85, v175 row_shr:2 row_mask:0xf bank_mask:0xf
	v_fmac_f32_dpp v148, v86, v176 row_shr:2 row_mask:0xf bank_mask:0xf
	v_fmac_f32_dpp v149, v87, v177 row_shr:2 row_mask:0xf bank_mask:0xf
	v_fmac_f32_dpp v254, v112, v190 row_ror:1 row_mask:0xf bank_mask:0x1
	v_fmac_f32_dpp v255, v113, v191 row_ror:1 row_mask:0xf bank_mask:0x1
	v_fmac_f32_dpp v148, v114, v192 row_ror:1 row_mask:0xf bank_mask:0x1
	v_fmac_f32_dpp v149, v115, v193 row_ror:1 row_mask:0xf bank_mask:0x1
	v_fmac_f32_dpp v254, v112, v174 row_ror:2 row_mask:0xf bank_mask:0x1
	v_fmac_f32_dpp v255, v113, v175 row_ror:2 row_mask:0xf bank_mask:0x1
	v_fmac_f32_dpp v148, v114, v176 row_ror:2 row_mask:0xf bank_mask:0x1
	v_fmac_f32_dpp v149, v115, v177 row_ror:2 row_mask:0xf bank_mask:0x1
	v_fma_f32 v246, |v254|, s38, 1.0
	v_fma_f32 v247, |v255|, s38, 1.0
	v_fma_f32 v248, |v148|, s38, 1.0
	v_fma_f32 v249, |v149|, s38, 1.0
	v_mul_f32_e32 v250, v254, v254
	v_mul_f32_e32 v251, v255, v255
	v_mul_f32_e32 v252, v148, v148
	v_mul_f32_e32 v253, v149, v149
	v_rcp_f32_e32 v246, v246
	v_rcp_f32_e32 v247, v247
	v_rcp_f32_e32 v248, v248
	v_rcp_f32_e32 v249, v249
	v_mul_f32_e32 v250, s72, v250
	v_mul_f32_e32 v251, s72, v251
	v_mul_f32_e32 v252, s72, v252
	v_mul_f32_e32 v253, s72, v253
	v_exp_f32_e32 v250, v250
;     __device__ __forceinline__ void operator()(const f32x4 (&acc)[2][2][4][2], const Unit& u, int wr, int wc, int fr, int fq) const {
;     ...
;                     if (!samp) {
;                         if ((blk & 31) != 0 && fr >= 14) hv = *(const f32x4*)(HALO + (size_t)(2 * blk + fr - 14) * FF2 + cgc);
;                         if ((u.pm & 7) == 7 && ai == 1 && wr == 1 && fr >= 14) *(f32x4*)(ncp + (size_t)((u.pm >> 3) * 2 + (fr - 14)) * FF2 + oc) = v[3];
;                     }
; #pragma unroll
;                     for (int m = 0; m < 4; ++m) {
;                         f32x4 cv;
;                         if (!samp) {
;                             const f32x4 prev = m ? v[m - 1] : hv;
; #pragma unroll
;                             for (int e = 0; e < 4; ++e) {
;                                 const int vi = __float_as_int(v[m][e]), pi = __float_as_int(prev[e]);
;                                 const int o1 = __builtin_amdgcn_mov_dpp(pi, 0x121, 0xf, 0xf, false);
;                                 const int o2 = __builtin_amdgcn_mov_dpp(pi, 0x122, 0xf, 0xf, false);
;                                 const float p1 = __int_as_float(__builtin_amdgcn_update_dpp(o1, vi, 0x111, 0xf, 0xf, false));
;                                 const float p2 = __int_as_float(__builtin_amdgcn_update_dpp(o2, vi, 0x112, 0xf, 0xf, false));
;                                 cv[e] = cb[e] + cw0[e] * p2 + cw1[e] * p1 + cw2[e] * v[m][e];
;                             }
;                         } else {
;                             const int ns = rowb + 16 * m + fr - MP;
;                             f32x4 s0 = (f32x4){0.f, 0.f, 0.f, 0.f}, s1 = s0;
;                             if (ns < NS) {
;                                 s0 = *(const f32x4*)(state + (size_t)(ns * 2 + 0) * FF2 + oc); s1 = *(const f32x4*)(state + (size_t)(ns * 2 + 1) * FF2 + oc);
;                                 *(f32x4*)(ncs + (size_t)(ns * 2 + 0) * FF2 + oc) = s1; *(f32x4*)(ncs + (size_t)(ns * 2 + 1) * FF2 + oc) = v[m];
;                             }
;                             cv = cb + cw0 * s0 + cw1 * s1 + cw2 * v[m];
;                         }
;                         if (bj == 0) cg[m] = gelu4(cv);
;                         else {
;                             const f32x4 r = cg[m] * cv;
;                             v2u w; w.x = cvt_pk_bf16(r[0], r[1]); w.y = cvt_pk_bf16(r[2], r[3]);
	v_exp_f32_e32 v251, v251
	v_exp_f32_e32 v252, v252
	v_exp_f32_e32 v253, v253
	v_fmamk_f32 v238, v246, 0x3f07dc22, v219
	v_fmamk_f32 v239, v247, 0x3f07dc22, v219
	v_fmamk_f32 v240, v248, 0x3f07dc22, v219
	v_fmamk_f32 v241, v249, 0x3f07dc22, v219
	v_fma_f32 v238, v246, v238, s66
	v_fma_f32 v239, v247, v239, s66
	v_fma_f32 v240, v248, v240, s66
	v_fma_f32 v241, v249, v241, s66
	v_fma_f32 v238, v246, v238, s68
	v_fma_f32 v239, v247, v239, s68
	v_fma_f32 v240, v248, v240, s68
	v_fma_f32 v241, v249, v241, s68
	v_fma_f32 v238, v246, v238, s70
	v_fma_f32 v239, v247, v239, s70
	v_fma_f32 v240, v248, v240, s70
	v_fma_f32 v241, v249, v241, s70
	v_mul_f32_e32 v238, v246, v238
	v_mul_f32_e32 v239, v247, v239
	v_mul_f32_e32 v240, v248, v240
	v_mul_f32_e32 v241, v249, v241
	v_mul_f32_e32 v238, v250, v238
	v_mul_f32_e32 v239, v251, v239
	v_mul_f32_e32 v240, v252, v240
	v_mul_f32_e32 v241, v253, v241
	v_max_f32_e32 v246, 0, v254
	v_max_f32_e32 v247, 0, v255
	v_max_f32_e32 v248, 0, v148
	v_max_f32_e32 v249, 0, v149
	v_fma_f32 v238, -|v254|, v238, v246
	v_fma_f32 v239, -|v255|, v239, v247
	v_fma_f32 v240, -|v148|, v240, v248
	v_fma_f32 v241, -|v149|, v241, v249
	v_mov_b32_dpp v112, v72 quad_perm:[0,1,2,3] row_mask:0xf bank_mask:0x8
	v_mov_b32_dpp v113, v73 quad_perm:[0,1,2,3] row_mask:0xf bank_mask:0x8
	v_mov_b32_dpp v114, v74 quad_perm:[0,1,2,3] row_mask:0xf bank_mask:0x8
	v_mov_b32_dpp v115, v75 quad_perm:[0,1,2,3] row_mask:0xf bank_mask:0x8
	v_pk_fma_f32 v[254:255], v[128:129], v[68:69], v[144:145]
	v_pk_fma_f32 v[148:149], v[130:131], v[70:71], v[146:147]
	v_fmac_f32_dpp v254, v68, v198 row_shr:1 row_mask:0xf bank_mask:0xf
	v_fmac_f32_dpp v255, v69, v199 row_shr:1 row_mask:0xf bank_mask:0xf
	v_fmac_f32_dpp v148, v70, v200 row_shr:1 row_mask:0xf bank_mask:0xf
	v_fmac_f32_dpp v149, v71, v201 row_shr:1 row_mask:0xf bank_mask:0xf
	v_fmac_f32_dpp v254, v68, v182 row_shr:2 row_mask:0xf bank_mask:0xf
	v_fmac_f32_dpp v255, v69, v183 row_shr:2 row_mask:0xf bank_mask:0xf
	v_fmac_f32_dpp v148, v70, v184 row_shr:2 row_mask:0xf bank_mask:0xf
	v_fmac_f32_dpp v149, v71, v185 row_shr:2 row_mask:0xf bank_mask:0xf
	v_fmac_f32_dpp v254, v112, v198 row_ror:1 row_mask:0xf bank_mask:0x1
	v_fmac_f32_dpp v255, v113, v199 row_ror:1 row_mask:0xf bank_mask:0x1
	v_fmac_f32_dpp v148, v114, v200 row_ror:1 row_mask:0xf bank_mask:0x1
	v_fmac_f32_dpp v149, v115, v201 row_ror:1 row_mask:0xf bank_mask:0x1
	v_fmac_f32_dpp v254, v112, v182 row_ror:2 row_mask:0xf bank_mask:0x1
	v_fmac_f32_dpp v255, v113, v183 row_ror:2 row_mask:0xf bank_mask:0x1
	v_fmac_f32_dpp v148, v114, v184 row_ror:2 row_mask:0xf bank_mask:0x1
	v_fmac_f32_dpp v149, v115, v185 row_ror:2 row_mask:0xf bank_mask:0x1
	v_pk_mul_f32 v[254:255], v[238:239], v[254:255]
	v_pk_mul_f32 v[148:149], v[240:241], v[148:149]
	v_cvt_pk_bf16_f32 v244, v254, v255
	v_cvt_pk_bf16_f32 v245, v148, v149
	s_add_u32 s56, s46, 0x2c000
	s_addc_u32 s57, s47, 0
	global_store_dwordx4 v151, v[242:245], s[56:57]
	v_mov_b32_e32 v220, 0
	v_mov_b32_e32 v221, 0
	v_mov_b32_e32 v222, 0
	v_mov_b32_e32 v223, 0
	v_mov_b32_e32 v116, 0
	v_mov_b32_e32 v117, 0
	v_mov_b32_e32 v118, 0
	v_mov_b32_e32 v119, 0
	v_mov_b32_e32 v84, 0
	v_mov_b32_e32 v85, 0
	v_mov_b32_e32 v86, 0
	v_mov_b32_e32 v87, 0
	v_mov_b32_e32 v100, 0
	v_mov_b32_e32 v101, 0
	v_mov_b32_e32 v102, 0
	v_mov_b32_e32 v103, 0
	v_mov_b32_e32 v68, 0
	v_mov_b32_e32 v69, 0
	v_mov_b32_e32 v70, 0
	v_mov_b32_e32 v71, 0
	s_and_b32 s14, s75, 31
	s_cselect_b64 s[92:93], -1, 0
	v_add_u32_e32 v246, 0x16000, v150
	s_and_b64 vcc, exec, s[86:87]
	s_cbranch_vccnz .Lfe_h0a
	s_mov_b64 s[14:15], exec
	s_mov_b64 exec, s[10:11]
	global_load_dwordx4 v[116:119], v246, s[44:45]
	global_load_dwordx4 v[84:87], v246, s[44:45] offset:16
	global_load_dwordx4 v[100:103], v246, s[44:45] offset:512
	global_load_dwordx4 v[68:71], v246, s[44:45] offset:528
	s_mov_b64 exec, s[14:15]
	s_and_b64 vcc, exec, s[92:93]
	s_cbranch_vccz .Lfe_h0a
	s_mov_b64 s[14:15], exec
	s_mov_b64 exec, s[10:11]
	global_load_dwordx4 v[220:223], v150, s[44:45]
	global_load_dwordx4 v[224:227], v150, s[44:45] offset:16
	global_load_dwordx4 v[228:231], v150, s[44:45] offset:512
	global_load_dwordx4 v[232:235], v150, s[44:45] offset:528
	s_mov_b64 exec, s[14:15]
.Lfe_h0a:
	v_mov_b32_dpp v112, v124 quad_perm:[0,1,2,3] row_mask:0xf bank_mask:0x8
	v_mov_b32_dpp v113, v125 quad_perm:[0,1,2,3] row_mask:0xf bank_mask:0x8
	v_mov_b32_dpp v114, v126 quad_perm:[0,1,2,3] row_mask:0xf bank_mask:0x8
	v_mov_b32_dpp v115, v127 quad_perm:[0,1,2,3] row_mask:0xf bank_mask:0x8
	v_pk_fma_f32 v[254:255], v[202:203], v[120:121], v[132:133]
	v_pk_fma_f32 v[148:149], v[204:205], v[122:123], v[134:135]
	v_fmac_f32_dpp v254, v120, v186 row_shr:1 row_mask:0xf bank_mask:0xf
	v_fmac_f32_dpp v255, v121, v187 row_shr:1 row_mask:0xf bank_mask:0xf
	v_fmac_f32_dpp v148, v122, v188 row_shr:1 row_mask:0xf bank_mask:0xf
	v_fmac_f32_dpp v149, v123, v189 row_shr:1 row_mask:0xf bank_mask:0xf
	v_fmac_f32_dpp v254, v120, v170 row_shr:2 row_mask:0xf bank_mask:0xf
	v_fmac_f32_dpp v255, v121, v171 row_shr:2 row_mask:0xf bank_mask:0xf
	v_fmac_f32_dpp v148, v122, v172 row_shr:2 row_mask:0xf bank_mask:0xf
	v_fmac_f32_dpp v149, v123, v173 row_shr:2 row_mask:0xf bank_mask:0xf
	v_fmac_f32_dpp v254, v112, v186 row_ror:1 row_mask:0xf bank_mask:0x1
	v_fmac_f32_dpp v255, v113, v187 row_ror:1 row_mask:0xf bank_mask:0x1
	v_fmac_f32_dpp v148, v114, v188 row_ror:1 row_mask:0xf bank_mask:0x1
	v_fmac_f32_dpp v149, v115, v189 row_ror:1 row_mask:0xf bank_mask:0x1
	v_fmac_f32_dpp v254, v112, v170 row_ror:2 row_mask:0xf bank_mask:0x1
	v_fmac_f32_dpp v255, v113, v171 row_ror:2 row_mask:0xf bank_mask:0x1
; __device__ __forceinline__ unsigned cvt_pk_bf16(float lo, float hi) { unsigned r; asm volatile("v_cvt_pk_bf16_f32 %0, %1, %2" : "=v"(r) : "v"(lo), "v"(hi)); return r; }
;     __device__ __forceinline__ void operator()(const f32x4 (&acc)[2][2][4][2], const Unit& u, int wr, int wc, int fr, int fq) const {
;     ...
; #pragma unroll
;                     for (int m = 0; m < 4; ++m) {
;                         f32x4 cv;
;                         if (!samp) {
;                             const f32x4 prev = m ? v[m - 1] : hv;
; #pragma unroll
;                             for (int e = 0; e < 4; ++e) {
;                                 const int vi = __float_as_int(v[m][e]), pi = __float_as_int(prev[e]);
;                                 const int o1 = __builtin_amdgcn_mov_dpp(pi, 0x121, 0xf, 0xf, false);
;                                 const int o2 = __builtin_amdgcn_mov_dpp(pi, 0x122, 0xf, 0xf, false);
;                                 const float p1 = __int_as_float(__builtin_amdgcn_update_dpp(o1, vi, 0x111, 0xf, 0xf, false));
;                                 const float p2 = __int_as_float(__builtin_amdgcn_update_dpp(o2, vi, 0x112, 0xf, 0xf, false));
;                                 cv[e] = cb[e] + cw0[e] * p2 + cw1[e] * p1 + cw2[e] * v[m][e];
;                             }
;                         } else {
;                             const int ns = rowb + 16 * m + fr - MP;
;                             f32x4 s0 = (f32x4){0.f, 0.f, 0.f, 0.f}, s1 = s0;
;                             if (ns < NS) {
;                                 s0 = *(const f32x4*)(state + (size_t)(ns * 2 + 0) * FF2 + oc); s1 = *(const f32x4*)(state + (size_t)(ns * 2 + 1) * FF2 + oc);
;                                 *(f32x4*)(ncs + (size_t)(ns * 2 + 0) * FF2 + oc) = s1; *(f32x4*)(ncs + (size_t)(ns * 2 + 1) * FF2 + oc) = v[m];
;                             }
;                             cv = cb + cw0 * s0 + cw1 * s1 + cw2 * v[m];
;                         }
;                         if (bj == 0) cg[m] = gelu4(cv);
;                         else {
;                             const f32x4 r = cg[m] * cv;
;                             v2u w; w.x = cvt_pk_bf16(r[0], r[1]); w.y = cvt_pk_bf16(r[2], r[3]);
;                             *(v2u*)(ACT + (size_t)(rowb + 16 * m + fr) * FF + 128 * u.pn + 32 * wc + 8 * fq + 4 * n) = w;
;                         }
	v_fmac_f32_dpp v148, v114, v172 row_ror:2 row_mask:0xf bank_mask:0x1
	v_fmac_f32_dpp v149, v115, v173 row_ror:2 row_mask:0xf bank_mask:0x1
	v_fma_f32 v246, |v254|, s38, 1.0
	v_fma_f32 v247, |v255|, s38, 1.0
	v_fma_f32 v248, |v148|, s38, 1.0
	v_fma_f32 v249, |v149|, s38, 1.0
	v_mul_f32_e32 v250, v254, v254
	v_mul_f32_e32 v251, v255, v255
	v_mul_f32_e32 v252, v148, v148
	v_mul_f32_e32 v253, v149, v149
	v_rcp_f32_e32 v246, v246
	v_rcp_f32_e32 v247, v247
	v_rcp_f32_e32 v248, v248
	v_rcp_f32_e32 v249, v249
	v_mul_f32_e32 v250, s72, v250
	v_mul_f32_e32 v251, s72, v251
	v_mul_f32_e32 v252, s72, v252
	v_mul_f32_e32 v253, s72, v253
	v_exp_f32_e32 v250, v250
	v_exp_f32_e32 v251, v251
	v_exp_f32_e32 v252, v252
	v_exp_f32_e32 v253, v253
	v_fmamk_f32 v238, v246, 0x3f07dc22, v219
	v_fmamk_f32 v239, v247, 0x3f07dc22, v219
	v_fmamk_f32 v240, v248, 0x3f07dc22, v219
	v_fmamk_f32 v241, v249, 0x3f07dc22, v219
	v_fma_f32 v238, v246, v238, s66
	v_fma_f32 v239, v247, v239, s66
	v_fma_f32 v240, v248, v240, s66
	v_fma_f32 v241, v249, v241, s66
	v_fma_f32 v238, v246, v238, s68
	v_fma_f32 v239, v247, v239, s68
	v_fma_f32 v240, v248, v240, s68
	v_fma_f32 v241, v249, v241, s68
	v_fma_f32 v238, v246, v238, s70
	v_fma_f32 v239, v247, v239, s70
	v_fma_f32 v240, v248, v240, s70
	v_fma_f32 v241, v249, v241, s70
	v_mul_f32_e32 v238, v246, v238
	v_mul_f32_e32 v239, v247, v239
	v_mul_f32_e32 v240, v248, v240
	v_mul_f32_e32 v241, v249, v241
	v_mul_f32_e32 v238, v250, v238
	v_mul_f32_e32 v239, v251, v239
	v_mul_f32_e32 v240, v252, v240
	v_mul_f32_e32 v241, v253, v241
	v_max_f32_e32 v246, 0, v254
	v_max_f32_e32 v247, 0, v255
	v_max_f32_e32 v248, 0, v148
	v_max_f32_e32 v249, 0, v149
	v_fma_f32 v238, -|v254|, v238, v246
	v_fma_f32 v239, -|v255|, v239, v247
	v_fma_f32 v240, -|v148|, v240, v248
	v_fma_f32 v241, -|v149|, v241, v249
	v_mov_b32_dpp v112, v108 quad_perm:[0,1,2,3] row_mask:0xf bank_mask:0x8
	v_mov_b32_dpp v113, v109 quad_perm:[0,1,2,3] row_mask:0xf bank_mask:0x8
	v_mov_b32_dpp v114, v110 quad_perm:[0,1,2,3] row_mask:0xf bank_mask:0x8
	v_mov_b32_dpp v115, v111 quad_perm:[0,1,2,3] row_mask:0xf bank_mask:0x8
	v_pk_fma_f32 v[254:255], v[210:211], v[104:105], v[140:141]
	v_pk_fma_f32 v[148:149], v[212:213], v[106:107], v[142:143]
	v_fmac_f32_dpp v254, v104, v194 row_shr:1 row_mask:0xf bank_mask:0xf
	v_fmac_f32_dpp v255, v105, v195 row_shr:1 row_mask:0xf bank_mask:0xf
	v_fmac_f32_dpp v148, v106, v196 row_shr:1 row_mask:0xf bank_mask:0xf
	v_fmac_f32_dpp v149, v107, v197 row_shr:1 row_mask:0xf bank_mask:0xf
	v_fmac_f32_dpp v254, v104, v178 row_shr:2 row_mask:0xf bank_mask:0xf
	v_fmac_f32_dpp v255, v105, v179 row_shr:2 row_mask:0xf bank_mask:0xf
	v_fmac_f32_dpp v148, v106, v180 row_shr:2 row_mask:0xf bank_mask:0xf
	v_fmac_f32_dpp v149, v107, v181 row_shr:2 row_mask:0xf bank_mask:0xf
	v_fmac_f32_dpp v254, v112, v194 row_ror:1 row_mask:0xf bank_mask:0x1
	v_fmac_f32_dpp v255, v113, v195 row_ror:1 row_mask:0xf bank_mask:0x1
	v_fmac_f32_dpp v148, v114, v196 row_ror:1 row_mask:0xf bank_mask:0x1
	v_fmac_f32_dpp v149, v115, v197 row_ror:1 row_mask:0xf bank_mask:0x1
	v_fmac_f32_dpp v254, v112, v178 row_ror:2 row_mask:0xf bank_mask:0x1
	v_fmac_f32_dpp v255, v113, v179 row_ror:2 row_mask:0xf bank_mask:0x1
	v_fmac_f32_dpp v148, v114, v180 row_ror:2 row_mask:0xf bank_mask:0x1
	v_fmac_f32_dpp v149, v115, v181 row_ror:2 row_mask:0xf bank_mask:0x1
	v_pk_mul_f32 v[254:255], v[238:239], v[254:255]
	v_pk_mul_f32 v[148:149], v[240:241], v[148:149]
	v_cvt_pk_bf16_f32 v242, v254, v255
	v_cvt_pk_bf16_f32 v243, v148, v149
	v_mov_b32_dpp v112, v92 quad_perm:[0,1,2,3] row_mask:0xf bank_mask:0x8
	v_mov_b32_dpp v113, v93 quad_perm:[0,1,2,3] row_mask:0xf bank_mask:0x8
	v_mov_b32_dpp v114, v94 quad_perm:[0,1,2,3] row_mask:0xf bank_mask:0x8
	v_mov_b32_dpp v115, v95 quad_perm:[0,1,2,3] row_mask:0xf bank_mask:0x8
	v_pk_fma_f32 v[254:255], v[206:207], v[88:89], v[136:137]
	v_pk_fma_f32 v[148:149], v[208:209], v[90:91], v[138:139]
	v_fmac_f32_dpp v254, v88, v190 row_shr:1 row_mask:0xf bank_mask:0xf
	v_fmac_f32_dpp v255, v89, v191 row_shr:1 row_mask:0xf bank_mask:0xf
	v_fmac_f32_dpp v148, v90, v192 row_shr:1 row_mask:0xf bank_mask:0xf
	v_fmac_f32_dpp v149, v91, v193 row_shr:1 row_mask:0xf bank_mask:0xf
	v_fmac_f32_dpp v254, v88, v174 row_shr:2 row_mask:0xf bank_mask:0xf
	v_fmac_f32_dpp v255, v89, v175 row_shr:2 row_mask:0xf bank_mask:0xf
	v_fmac_f32_dpp v148, v90, v176 row_shr:2 row_mask:0xf bank_mask:0xf
	v_fmac_f32_dpp v149, v91, v177 row_shr:2 row_mask:0xf bank_mask:0xf
	v_fmac_f32_dpp v254, v112, v190 row_ror:1 row_mask:0xf bank_mask:0x1
	v_fmac_f32_dpp v255, v113, v191 row_ror:1 row_mask:0xf bank_mask:0x1
	v_fmac_f32_dpp v148, v114, v192 row_ror:1 row_mask:0xf bank_mask:0x1
	v_fmac_f32_dpp v149, v115, v193 row_ror:1 row_mask:0xf bank_mask:0x1
	v_fmac_f32_dpp v254, v112, v174 row_ror:2 row_mask:0xf bank_mask:0x1
	v_fmac_f32_dpp v255, v113, v175 row_ror:2 row_mask:0xf bank_mask:0x1
	v_fmac_f32_dpp v148, v114, v176 row_ror:2 row_mask:0xf bank_mask:0x1
	v_fmac_f32_dpp v149, v115, v177 row_ror:2 row_mask:0xf bank_mask:0x1
	v_fma_f32 v246, |v254|, s38, 1.0
	v_fma_f32 v247, |v255|, s38, 1.0
	v_fma_f32 v248, |v148|, s38, 1.0
	v_fma_f32 v249, |v149|, s38, 1.0
	v_mul_f32_e32 v250, v254, v254
	v_mul_f32_e32 v251, v255, v255
	v_mul_f32_e32 v252, v148, v148
	v_mul_f32_e32 v253, v149, v149
	v_rcp_f32_e32 v246, v246
	v_rcp_f32_e32 v247, v247
	v_rcp_f32_e32 v248, v248
	v_rcp_f32_e32 v249, v249
	v_mul_f32_e32 v250, s72, v250
	v_mul_f32_e32 v251, s72, v251
	v_mul_f32_e32 v252, s72, v252
	v_mul_f32_e32 v253, s72, v253
	v_exp_f32_e32 v250, v250
	v_exp_f32_e32 v251, v251
	v_exp_f32_e32 v252, v252
	v_exp_f32_e32 v253, v253
; __device__ __forceinline__ unsigned cvt_pk_bf16(float lo, float hi) { unsigned r; asm volatile("v_cvt_pk_bf16_f32 %0, %1, %2" : "=v"(r) : "v"(lo), "v"(hi)); return r; }
;     __device__ __forceinline__ void operator()(const f32x4 (&acc)[2][2][4][2], const Unit& u, int wr, int wc, int fr, int fq) const {
;     ...
; #pragma unroll
;                     for (int m = 0; m < 4; ++m) {
;                         f32x4 cv;
;                         if (!samp) {
;                             const f32x4 prev = m ? v[m - 1] : hv;
; #pragma unroll
;                             for (int e = 0; e < 4; ++e) {
;                                 const int vi = __float_as_int(v[m][e]), pi = __float_as_int(prev[e]);
;                                 const int o1 = __builtin_amdgcn_mov_dpp(pi, 0x121, 0xf, 0xf, false);
;                                 const int o2 = __builtin_amdgcn_mov_dpp(pi, 0x122, 0xf, 0xf, false);
;                                 const float p1 = __int_as_float(__builtin_amdgcn_update_dpp(o1, vi, 0x111, 0xf, 0xf, false));
;                                 const float p2 = __int_as_float(__builtin_amdgcn_update_dpp(o2, vi, 0x112, 0xf, 0xf, false));
;                                 cv[e] = cb[e] + cw0[e] * p2 + cw1[e] * p1 + cw2[e] * v[m][e];
;                             }
;                         } else {
;                             const int ns = rowb + 16 * m + fr - MP;
;                             f32x4 s0 = (f32x4){0.f, 0.f, 0.f, 0.f}, s1 = s0;
;                             if (ns < NS) {
;                                 s0 = *(const f32x4*)(state + (size_t)(ns * 2 + 0) * FF2 + oc); s1 = *(const f32x4*)(state + (size_t)(ns * 2 + 1) * FF2 + oc);
;                                 *(f32x4*)(ncs + (size_t)(ns * 2 + 0) * FF2 + oc) = s1; *(f32x4*)(ncs + (size_t)(ns * 2 + 1) * FF2 + oc) = v[m];
;                             }
;                             cv = cb + cw0 * s0 + cw1 * s1 + cw2 * v[m];
;                         }
;                         if (bj == 0) cg[m] = gelu4(cv);
;                         else {
;                             const f32x4 r = cg[m] * cv;
;                             v2u w; w.x = cvt_pk_bf16(r[0], r[1]); w.y = cvt_pk_bf16(r[2], r[3]);
;                             *(v2u*)(ACT + (size_t)(rowb + 16 * m + fr) * FF + 128 * u.pn + 32 * wc + 8 * fq + 4 * n) = w;
;                         }
	v_fmamk_f32 v238, v246, 0x3f07dc22, v219
	v_fmamk_f32 v239, v247, 0x3f07dc22, v219
	v_fmamk_f32 v240, v248, 0x3f07dc22, v219
	v_fmamk_f32 v241, v249, 0x3f07dc22, v219
	v_fma_f32 v238, v246, v238, s66
	v_fma_f32 v239, v247, v239, s66
	v_fma_f32 v240, v248, v240, s66
	v_fma_f32 v241, v249, v241, s66
	v_fma_f32 v238, v246, v238, s68
	v_fma_f32 v239, v247, v239, s68
	v_fma_f32 v240, v248, v240, s68
	v_fma_f32 v241, v249, v241, s68
	v_fma_f32 v238, v246, v238, s70
	v_fma_f32 v239, v247, v239, s70
	v_fma_f32 v240, v248, v240, s70
	v_fma_f32 v241, v249, v241, s70
	v_mul_f32_e32 v238, v246, v238
	v_mul_f32_e32 v239, v247, v239
	v_mul_f32_e32 v240, v248, v240
	v_mul_f32_e32 v241, v249, v241
	v_mul_f32_e32 v238, v250, v238
	v_mul_f32_e32 v239, v251, v239
	v_mul_f32_e32 v240, v252, v240
	v_mul_f32_e32 v241, v253, v241
	v_max_f32_e32 v246, 0, v254
	v_max_f32_e32 v247, 0, v255
	v_max_f32_e32 v248, 0, v148
	v_max_f32_e32 v249, 0, v149
	v_fma_f32 v238, -|v254|, v238, v246
	v_fma_f32 v239, -|v255|, v239, v247
	v_fma_f32 v240, -|v148|, v240, v248
	v_fma_f32 v241, -|v149|, v241, v249
	v_mov_b32_dpp v112, v76 quad_perm:[0,1,2,3] row_mask:0xf bank_mask:0x8
	v_mov_b32_dpp v113, v77 quad_perm:[0,1,2,3] row_mask:0xf bank_mask:0x8
	v_mov_b32_dpp v114, v78 quad_perm:[0,1,2,3] row_mask:0xf bank_mask:0x8
	v_mov_b32_dpp v115, v79 quad_perm:[0,1,2,3] row_mask:0xf bank_mask:0x8
	v_pk_fma_f32 v[254:255], v[128:129], v[72:73], v[144:145]
	v_pk_fma_f32 v[148:149], v[130:131], v[74:75], v[146:147]
	v_fmac_f32_dpp v254, v72, v198 row_shr:1 row_mask:0xf bank_mask:0xf
	v_fmac_f32_dpp v255, v73, v199 row_shr:1 row_mask:0xf bank_mask:0xf
	v_fmac_f32_dpp v148, v74, v200 row_shr:1 row_mask:0xf bank_mask:0xf
	v_fmac_f32_dpp v149, v75, v201 row_shr:1 row_mask:0xf bank_mask:0xf
	v_fmac_f32_dpp v254, v72, v182 row_shr:2 row_mask:0xf bank_mask:0xf
	v_fmac_f32_dpp v255, v73, v183 row_shr:2 row_mask:0xf bank_mask:0xf
	v_fmac_f32_dpp v148, v74, v184 row_shr:2 row_mask:0xf bank_mask:0xf
	v_fmac_f32_dpp v149, v75, v185 row_shr:2 row_mask:0xf bank_mask:0xf
	v_fmac_f32_dpp v254, v112, v198 row_ror:1 row_mask:0xf bank_mask:0x1
	v_fmac_f32_dpp v255, v113, v199 row_ror:1 row_mask:0xf bank_mask:0x1
	v_fmac_f32_dpp v148, v114, v200 row_ror:1 row_mask:0xf bank_mask:0x1
	v_fmac_f32_dpp v149, v115, v201 row_ror:1 row_mask:0xf bank_mask:0x1
	v_fmac_f32_dpp v254, v112, v182 row_ror:2 row_mask:0xf bank_mask:0x1
	v_fmac_f32_dpp v255, v113, v183 row_ror:2 row_mask:0xf bank_mask:0x1
	v_fmac_f32_dpp v148, v114, v184 row_ror:2 row_mask:0xf bank_mask:0x1
	v_fmac_f32_dpp v149, v115, v185 row_ror:2 row_mask:0xf bank_mask:0x1
	v_pk_mul_f32 v[254:255], v[238:239], v[254:255]
	v_pk_mul_f32 v[148:149], v[240:241], v[148:149]
	v_cvt_pk_bf16_f32 v244, v254, v255
	v_cvt_pk_bf16_f32 v245, v148, v149
	s_add_u32 s56, s46, 0x16000
	s_addc_u32 s57, s47, 0
	global_store_dwordx4 v151, v[242:245], s[56:57]
	v_mov_b32_dpp v112, v48 quad_perm:[0,1,2,3] row_mask:0xf bank_mask:0x8
	v_mov_b32_dpp v113, v49 quad_perm:[0,1,2,3] row_mask:0xf bank_mask:0x8
	v_mov_b32_dpp v114, v50 quad_perm:[0,1,2,3] row_mask:0xf bank_mask:0x8
	v_mov_b32_dpp v115, v51 quad_perm:[0,1,2,3] row_mask:0xf bank_mask:0x8
	v_pk_fma_f32 v[254:255], v[202:203], v[56:57], v[132:133]
	v_pk_fma_f32 v[148:149], v[204:205], v[58:59], v[134:135]
	v_fmac_f32_dpp v254, v56, v186 row_shr:1 row_mask:0xf bank_mask:0xf
	v_fmac_f32_dpp v255, v57, v187 row_shr:1 row_mask:0xf bank_mask:0xf
	v_fmac_f32_dpp v148, v58, v188 row_shr:1 row_mask:0xf bank_mask:0xf
	v_fmac_f32_dpp v149, v59, v189 row_shr:1 row_mask:0xf bank_mask:0xf
	v_fmac_f32_dpp v254, v56, v170 row_shr:2 row_mask:0xf bank_mask:0xf
	v_fmac_f32_dpp v255, v57, v171 row_shr:2 row_mask:0xf bank_mask:0xf
	v_fmac_f32_dpp v148, v58, v172 row_shr:2 row_mask:0xf bank_mask:0xf
	v_fmac_f32_dpp v149, v59, v173 row_shr:2 row_mask:0xf bank_mask:0xf
	v_fmac_f32_dpp v254, v112, v186 row_ror:1 row_mask:0xf bank_mask:0x1
	v_fmac_f32_dpp v255, v113, v187 row_ror:1 row_mask:0xf bank_mask:0x1
	v_fmac_f32_dpp v148, v114, v188 row_ror:1 row_mask:0xf bank_mask:0x1
	v_fmac_f32_dpp v149, v115, v189 row_ror:1 row_mask:0xf bank_mask:0x1
	v_fmac_f32_dpp v254, v112, v170 row_ror:2 row_mask:0xf bank_mask:0x1
	v_fmac_f32_dpp v255, v113, v171 row_ror:2 row_mask:0xf bank_mask:0x1
	v_fmac_f32_dpp v148, v114, v172 row_ror:2 row_mask:0xf bank_mask:0x1
	v_fmac_f32_dpp v149, v115, v173 row_ror:2 row_mask:0xf bank_mask:0x1
	v_fma_f32 v246, |v254|, s38, 1.0
	v_fma_f32 v247, |v255|, s38, 1.0
	v_fma_f32 v248, |v148|, s38, 1.0
	v_fma_f32 v249, |v149|, s38, 1.0
	v_mul_f32_e32 v250, v254, v254
	v_mul_f32_e32 v251, v255, v255
	v_mul_f32_e32 v252, v148, v148
	v_mul_f32_e32 v253, v149, v149
	v_rcp_f32_e32 v246, v246
	v_rcp_f32_e32 v247, v247
	v_rcp_f32_e32 v248, v248
	v_rcp_f32_e32 v249, v249
	v_mul_f32_e32 v250, s72, v250
	v_mul_f32_e32 v251, s72, v251
	v_mul_f32_e32 v252, s72, v252
	v_mul_f32_e32 v253, s72, v253
	v_exp_f32_e32 v250, v250
	v_exp_f32_e32 v251, v251
	v_exp_f32_e32 v252, v252
	v_exp_f32_e32 v253, v253
	v_fmamk_f32 v238, v246, 0x3f07dc22, v219
	v_fmamk_f32 v239, v247, 0x3f07dc22, v219
	v_fmamk_f32 v240, v248, 0x3f07dc22, v219
	v_fmamk_f32 v241, v249, 0x3f07dc22, v219
	v_fma_f32 v238, v246, v238, s66
	v_fma_f32 v239, v247, v239, s66
	v_fma_f32 v240, v248, v240, s66
	v_fma_f32 v241, v249, v241, s66
	v_fma_f32 v238, v246, v238, s68
	v_fma_f32 v239, v247, v239, s68
	v_fma_f32 v240, v248, v240, s68
	v_fma_f32 v241, v249, v241, s68
	v_fma_f32 v238, v246, v238, s70
	v_fma_f32 v239, v247, v239, s70
	v_fma_f32 v240, v248, v240, s70
	v_fma_f32 v241, v249, v241, s70
	v_mul_f32_e32 v238, v246, v238
	v_mul_f32_e32 v239, v247, v239
	v_mul_f32_e32 v240, v248, v240
; __device__ __forceinline__ unsigned cvt_pk_bf16(float lo, float hi) { unsigned r; asm volatile("v_cvt_pk_bf16_f32 %0, %1, %2" : "=v"(r) : "v"(lo), "v"(hi)); return r; }
;     __device__ __forceinline__ void operator()(const f32x4 (&acc)[2][2][4][2], const Unit& u, int wr, int wc, int fr, int fq) const {
;     ...
; #pragma unroll
;                     for (int m = 0; m < 4; ++m) {
;                         f32x4 cv;
;                         if (!samp) {
;                             const f32x4 prev = m ? v[m - 1] : hv;
; #pragma unroll
;                             for (int e = 0; e < 4; ++e) {
;                                 const int vi = __float_as_int(v[m][e]), pi = __float_as_int(prev[e]);
;                                 const int o1 = __builtin_amdgcn_mov_dpp(pi, 0x121, 0xf, 0xf, false);
;                                 const int o2 = __builtin_amdgcn_mov_dpp(pi, 0x122, 0xf, 0xf, false);
;                                 const float p1 = __int_as_float(__builtin_amdgcn_update_dpp(o1, vi, 0x111, 0xf, 0xf, false));
;                                 const float p2 = __int_as_float(__builtin_amdgcn_update_dpp(o2, vi, 0x112, 0xf, 0xf, false));
;                                 cv[e] = cb[e] + cw0[e] * p2 + cw1[e] * p1 + cw2[e] * v[m][e];
;                             }
;                         } else {
;                             const int ns = rowb + 16 * m + fr - MP;
;                             f32x4 s0 = (f32x4){0.f, 0.f, 0.f, 0.f}, s1 = s0;
;                             if (ns < NS) {
;                                 s0 = *(const f32x4*)(state + (size_t)(ns * 2 + 0) * FF2 + oc); s1 = *(const f32x4*)(state + (size_t)(ns * 2 + 1) * FF2 + oc);
;                                 *(f32x4*)(ncs + (size_t)(ns * 2 + 0) * FF2 + oc) = s1; *(f32x4*)(ncs + (size_t)(ns * 2 + 1) * FF2 + oc) = v[m];
;                             }
;                             cv = cb + cw0 * s0 + cw1 * s1 + cw2 * v[m];
;                         }
;                         if (bj == 0) cg[m] = gelu4(cv);
;                         else {
;                             const f32x4 r = cg[m] * cv;
;                             v2u w; w.x = cvt_pk_bf16(r[0], r[1]); w.y = cvt_pk_bf16(r[2], r[3]);
;                             *(v2u*)(ACT + (size_t)(rowb + 16 * m + fr) * FF + 128 * u.pn + 32 * wc + 8 * fq + 4 * n) = w;
;                         }
	v_mul_f32_e32 v241, v249, v241
	v_mul_f32_e32 v238, v250, v238
	v_mul_f32_e32 v239, v251, v239
	v_mul_f32_e32 v240, v252, v240
	v_mul_f32_e32 v241, v253, v241
	v_max_f32_e32 v246, 0, v254
	v_max_f32_e32 v247, 0, v255
	v_max_f32_e32 v248, 0, v148
	v_max_f32_e32 v249, 0, v149
	v_fma_f32 v238, -|v254|, v238, v246
	v_fma_f32 v239, -|v255|, v239, v247
	v_fma_f32 v240, -|v148|, v240, v248
	v_fma_f32 v241, -|v149|, v241, v249
	v_mov_b32_dpp v112, v32 quad_perm:[0,1,2,3] row_mask:0xf bank_mask:0x8
	v_mov_b32_dpp v113, v33 quad_perm:[0,1,2,3] row_mask:0xf bank_mask:0x8
	v_mov_b32_dpp v114, v34 quad_perm:[0,1,2,3] row_mask:0xf bank_mask:0x8
	v_mov_b32_dpp v115, v35 quad_perm:[0,1,2,3] row_mask:0xf bank_mask:0x8
	v_pk_fma_f32 v[254:255], v[210:211], v[40:41], v[140:141]
	v_pk_fma_f32 v[148:149], v[212:213], v[42:43], v[142:143]
	v_fmac_f32_dpp v254, v40, v194 row_shr:1 row_mask:0xf bank_mask:0xf
	v_fmac_f32_dpp v255, v41, v195 row_shr:1 row_mask:0xf bank_mask:0xf
	v_fmac_f32_dpp v148, v42, v196 row_shr:1 row_mask:0xf bank_mask:0xf
	v_fmac_f32_dpp v149, v43, v197 row_shr:1 row_mask:0xf bank_mask:0xf
	v_fmac_f32_dpp v254, v40, v178 row_shr:2 row_mask:0xf bank_mask:0xf
	v_fmac_f32_dpp v255, v41, v179 row_shr:2 row_mask:0xf bank_mask:0xf
	v_fmac_f32_dpp v148, v42, v180 row_shr:2 row_mask:0xf bank_mask:0xf
	v_fmac_f32_dpp v149, v43, v181 row_shr:2 row_mask:0xf bank_mask:0xf
	v_fmac_f32_dpp v254, v112, v194 row_ror:1 row_mask:0xf bank_mask:0x1
	v_fmac_f32_dpp v255, v113, v195 row_ror:1 row_mask:0xf bank_mask:0x1
	v_fmac_f32_dpp v148, v114, v196 row_ror:1 row_mask:0xf bank_mask:0x1
	v_fmac_f32_dpp v149, v115, v197 row_ror:1 row_mask:0xf bank_mask:0x1
	v_fmac_f32_dpp v254, v112, v178 row_ror:2 row_mask:0xf bank_mask:0x1
	v_fmac_f32_dpp v255, v113, v179 row_ror:2 row_mask:0xf bank_mask:0x1
	v_fmac_f32_dpp v148, v114, v180 row_ror:2 row_mask:0xf bank_mask:0x1
	v_fmac_f32_dpp v149, v115, v181 row_ror:2 row_mask:0xf bank_mask:0x1
	v_pk_mul_f32 v[254:255], v[238:239], v[254:255]
	v_pk_mul_f32 v[148:149], v[240:241], v[148:149]
	v_cvt_pk_bf16_f32 v242, v254, v255
	v_cvt_pk_bf16_f32 v243, v148, v149
	v_mov_b32_dpp v112, v16 quad_perm:[0,1,2,3] row_mask:0xf bank_mask:0x8
	v_mov_b32_dpp v113, v17 quad_perm:[0,1,2,3] row_mask:0xf bank_mask:0x8
	v_mov_b32_dpp v114, v18 quad_perm:[0,1,2,3] row_mask:0xf bank_mask:0x8
	v_mov_b32_dpp v115, v19 quad_perm:[0,1,2,3] row_mask:0xf bank_mask:0x8
	v_pk_fma_f32 v[254:255], v[206:207], v[24:25], v[136:137]
	v_pk_fma_f32 v[148:149], v[208:209], v[26:27], v[138:139]
	v_fmac_f32_dpp v254, v24, v190 row_shr:1 row_mask:0xf bank_mask:0xf
	v_fmac_f32_dpp v255, v25, v191 row_shr:1 row_mask:0xf bank_mask:0xf
	v_fmac_f32_dpp v148, v26, v192 row_shr:1 row_mask:0xf bank_mask:0xf
	v_fmac_f32_dpp v149, v27, v193 row_shr:1 row_mask:0xf bank_mask:0xf
	v_fmac_f32_dpp v254, v24, v174 row_shr:2 row_mask:0xf bank_mask:0xf
	v_fmac_f32_dpp v255, v25, v175 row_shr:2 row_mask:0xf bank_mask:0xf
	v_fmac_f32_dpp v148, v26, v176 row_shr:2 row_mask:0xf bank_mask:0xf
	v_fmac_f32_dpp v149, v27, v177 row_shr:2 row_mask:0xf bank_mask:0xf
	v_fmac_f32_dpp v254, v112, v190 row_ror:1 row_mask:0xf bank_mask:0x1
	v_fmac_f32_dpp v255, v113, v191 row_ror:1 row_mask:0xf bank_mask:0x1
	v_fmac_f32_dpp v148, v114, v192 row_ror:1 row_mask:0xf bank_mask:0x1
	v_fmac_f32_dpp v149, v115, v193 row_ror:1 row_mask:0xf bank_mask:0x1
	v_fmac_f32_dpp v254, v112, v174 row_ror:2 row_mask:0xf bank_mask:0x1
	v_fmac_f32_dpp v255, v113, v175 row_ror:2 row_mask:0xf bank_mask:0x1
	v_fmac_f32_dpp v148, v114, v176 row_ror:2 row_mask:0xf bank_mask:0x1
	v_fmac_f32_dpp v149, v115, v177 row_ror:2 row_mask:0xf bank_mask:0x1
	v_fma_f32 v246, |v254|, s38, 1.0
	v_fma_f32 v247, |v255|, s38, 1.0
	v_fma_f32 v248, |v148|, s38, 1.0
	v_fma_f32 v249, |v149|, s38, 1.0
	v_mul_f32_e32 v250, v254, v254
	v_mul_f32_e32 v251, v255, v255
	v_mul_f32_e32 v252, v148, v148
	v_mul_f32_e32 v253, v149, v149
	v_rcp_f32_e32 v246, v246
	v_rcp_f32_e32 v247, v247
	v_rcp_f32_e32 v248, v248
	v_rcp_f32_e32 v249, v249
	v_mul_f32_e32 v250, s72, v250
	v_mul_f32_e32 v251, s72, v251
	v_mul_f32_e32 v252, s72, v252
	v_mul_f32_e32 v253, s72, v253
	v_exp_f32_e32 v250, v250
	v_exp_f32_e32 v251, v251
	v_exp_f32_e32 v252, v252
	v_exp_f32_e32 v253, v253
	v_fmamk_f32 v238, v246, 0x3f07dc22, v219
	v_fmamk_f32 v239, v247, 0x3f07dc22, v219
	v_fmamk_f32 v240, v248, 0x3f07dc22, v219
	v_fmamk_f32 v241, v249, 0x3f07dc22, v219
	v_fma_f32 v238, v246, v238, s66
	v_fma_f32 v239, v247, v239, s66
	v_fma_f32 v240, v248, v240, s66
	v_fma_f32 v241, v249, v241, s66
	v_fma_f32 v238, v246, v238, s68
	v_fma_f32 v239, v247, v239, s68
	v_fma_f32 v240, v248, v240, s68
	v_fma_f32 v241, v249, v241, s68
	v_fma_f32 v238, v246, v238, s70
	v_fma_f32 v239, v247, v239, s70
	v_fma_f32 v240, v248, v240, s70
	v_fma_f32 v241, v249, v241, s70
	v_mul_f32_e32 v238, v246, v238
	v_mul_f32_e32 v239, v247, v239
	v_mul_f32_e32 v240, v248, v240
	v_mul_f32_e32 v241, v249, v241
	v_mul_f32_e32 v238, v250, v238
	v_mul_f32_e32 v239, v251, v239
	v_mul_f32_e32 v240, v252, v240
	v_mul_f32_e32 v241, v253, v241
	v_max_f32_e32 v246, 0, v254
	v_max_f32_e32 v247, 0, v255
	v_max_f32_e32 v248, 0, v148
	v_max_f32_e32 v249, 0, v149
	v_fma_f32 v238, -|v254|, v238, v246
	v_fma_f32 v239, -|v255|, v239, v247
	v_fma_f32 v240, -|v148|, v240, v248
	v_fma_f32 v241, -|v149|, v241, v249
	v_mov_b32_dpp v112, v0 quad_perm:[0,1,2,3] row_mask:0xf bank_mask:0x8
	v_mov_b32_dpp v113, v1 quad_perm:[0,1,2,3] row_mask:0xf bank_mask:0x8
	v_mov_b32_dpp v114, v2 quad_perm:[0,1,2,3] row_mask:0xf bank_mask:0x8
	v_mov_b32_dpp v115, v3 quad_perm:[0,1,2,3] row_mask:0xf bank_mask:0x8
	v_pk_fma_f32 v[254:255], v[128:129], v[8:9], v[144:145]
; __device__ __forceinline__ unsigned cvt_pk_bf16(float lo, float hi) { unsigned r; asm volatile("v_cvt_pk_bf16_f32 %0, %1, %2" : "=v"(r) : "v"(lo), "v"(hi)); return r; }
;     __device__ __forceinline__ void operator()(const f32x4 (&acc)[2][2][4][2], const Unit& u, int wr, int wc, int fr, int fq) const {
;     ...
; #pragma unroll
;                     for (int m = 0; m < 4; ++m) {
;                         f32x4 cv;
;                         if (!samp) {
;                             const f32x4 prev = m ? v[m - 1] : hv;
; #pragma unroll
;                             for (int e = 0; e < 4; ++e) {
;                                 const int vi = __float_as_int(v[m][e]), pi = __float_as_int(prev[e]);
;                                 const int o1 = __builtin_amdgcn_mov_dpp(pi, 0x121, 0xf, 0xf, false);
;                                 const int o2 = __builtin_amdgcn_mov_dpp(pi, 0x122, 0xf, 0xf, false);
;                                 const float p1 = __int_as_float(__builtin_amdgcn_update_dpp(o1, vi, 0x111, 0xf, 0xf, false));
;                                 const float p2 = __int_as_float(__builtin_amdgcn_update_dpp(o2, vi, 0x112, 0xf, 0xf, false));
;                                 cv[e] = cb[e] + cw0[e] * p2 + cw1[e] * p1 + cw2[e] * v[m][e];
;                             }
;                         } else {
;                             const int ns = rowb + 16 * m + fr - MP;
;                             f32x4 s0 = (f32x4){0.f, 0.f, 0.f, 0.f}, s1 = s0;
;                             if (ns < NS) {
;                                 s0 = *(const f32x4*)(state + (size_t)(ns * 2 + 0) * FF2 + oc); s1 = *(const f32x4*)(state + (size_t)(ns * 2 + 1) * FF2 + oc);
;                                 *(f32x4*)(ncs + (size_t)(ns * 2 + 0) * FF2 + oc) = s1; *(f32x4*)(ncs + (size_t)(ns * 2 + 1) * FF2 + oc) = v[m];
;                             }
;                             cv = cb + cw0 * s0 + cw1 * s1 + cw2 * v[m];
;                         }
;                         if (bj == 0) cg[m] = gelu4(cv);
;                         else {
;                             const f32x4 r = cg[m] * cv;
;                             v2u w; w.x = cvt_pk_bf16(r[0], r[1]); w.y = cvt_pk_bf16(r[2], r[3]);
;                             *(v2u*)(ACT + (size_t)(rowb + 16 * m + fr) * FF + 128 * u.pn + 32 * wc + 8 * fq + 4 * n) = w;
;                         }
	v_pk_fma_f32 v[148:149], v[130:131], v[10:11], v[146:147]
	v_fmac_f32_dpp v254, v8, v198 row_shr:1 row_mask:0xf bank_mask:0xf
	v_fmac_f32_dpp v255, v9, v199 row_shr:1 row_mask:0xf bank_mask:0xf
	v_fmac_f32_dpp v148, v10, v200 row_shr:1 row_mask:0xf bank_mask:0xf
	v_fmac_f32_dpp v149, v11, v201 row_shr:1 row_mask:0xf bank_mask:0xf
	v_fmac_f32_dpp v254, v8, v182 row_shr:2 row_mask:0xf bank_mask:0xf
	v_fmac_f32_dpp v255, v9, v183 row_shr:2 row_mask:0xf bank_mask:0xf
	v_fmac_f32_dpp v148, v10, v184 row_shr:2 row_mask:0xf bank_mask:0xf
	v_fmac_f32_dpp v149, v11, v185 row_shr:2 row_mask:0xf bank_mask:0xf
	v_fmac_f32_dpp v254, v112, v198 row_ror:1 row_mask:0xf bank_mask:0x1
	v_fmac_f32_dpp v255, v113, v199 row_ror:1 row_mask:0xf bank_mask:0x1
	v_fmac_f32_dpp v148, v114, v200 row_ror:1 row_mask:0xf bank_mask:0x1
	v_fmac_f32_dpp v149, v115, v201 row_ror:1 row_mask:0xf bank_mask:0x1
	v_fmac_f32_dpp v254, v112, v182 row_ror:2 row_mask:0xf bank_mask:0x1
	v_fmac_f32_dpp v255, v113, v183 row_ror:2 row_mask:0xf bank_mask:0x1
	v_fmac_f32_dpp v148, v114, v184 row_ror:2 row_mask:0xf bank_mask:0x1
	v_fmac_f32_dpp v149, v115, v185 row_ror:2 row_mask:0xf bank_mask:0x1
	v_pk_mul_f32 v[254:255], v[238:239], v[254:255]
	v_pk_mul_f32 v[148:149], v[240:241], v[148:149]
	v_cvt_pk_bf16_f32 v244, v254, v255
	v_cvt_pk_bf16_f32 v245, v148, v149
	s_add_u32 s56, s46, 0xf2000
	s_addc_u32 s57, s47, 0
	global_store_dwordx4 v151, v[242:245], s[56:57]
	v_mov_b32_dpp v112, v52 quad_perm:[0,1,2,3] row_mask:0xf bank_mask:0x8
	v_mov_b32_dpp v113, v53 quad_perm:[0,1,2,3] row_mask:0xf bank_mask:0x8
	v_mov_b32_dpp v114, v54 quad_perm:[0,1,2,3] row_mask:0xf bank_mask:0x8
	v_mov_b32_dpp v115, v55 quad_perm:[0,1,2,3] row_mask:0xf bank_mask:0x8
	v_pk_fma_f32 v[254:255], v[202:203], v[48:49], v[132:133]
	v_pk_fma_f32 v[148:149], v[204:205], v[50:51], v[134:135]
	v_fmac_f32_dpp v254, v48, v186 row_shr:1 row_mask:0xf bank_mask:0xf
	v_fmac_f32_dpp v255, v49, v187 row_shr:1 row_mask:0xf bank_mask:0xf
	v_fmac_f32_dpp v148, v50, v188 row_shr:1 row_mask:0xf bank_mask:0xf
	v_fmac_f32_dpp v149, v51, v189 row_shr:1 row_mask:0xf bank_mask:0xf
	v_fmac_f32_dpp v254, v48, v170 row_shr:2 row_mask:0xf bank_mask:0xf
	v_fmac_f32_dpp v255, v49, v171 row_shr:2 row_mask:0xf bank_mask:0xf
	v_fmac_f32_dpp v148, v50, v172 row_shr:2 row_mask:0xf bank_mask:0xf
	v_fmac_f32_dpp v149, v51, v173 row_shr:2 row_mask:0xf bank_mask:0xf
	v_fmac_f32_dpp v254, v112, v186 row_ror:1 row_mask:0xf bank_mask:0x1
	v_fmac_f32_dpp v255, v113, v187 row_ror:1 row_mask:0xf bank_mask:0x1
	v_fmac_f32_dpp v148, v114, v188 row_ror:1 row_mask:0xf bank_mask:0x1
	v_fmac_f32_dpp v149, v115, v189 row_ror:1 row_mask:0xf bank_mask:0x1
	v_fmac_f32_dpp v254, v112, v170 row_ror:2 row_mask:0xf bank_mask:0x1
	v_fmac_f32_dpp v255, v113, v171 row_ror:2 row_mask:0xf bank_mask:0x1
	v_fmac_f32_dpp v148, v114, v172 row_ror:2 row_mask:0xf bank_mask:0x1
	v_fmac_f32_dpp v149, v115, v173 row_ror:2 row_mask:0xf bank_mask:0x1
	v_fma_f32 v246, |v254|, s38, 1.0
	v_fma_f32 v247, |v255|, s38, 1.0
	v_fma_f32 v248, |v148|, s38, 1.0
	v_fma_f32 v249, |v149|, s38, 1.0
	v_mul_f32_e32 v250, v254, v254
	v_mul_f32_e32 v251, v255, v255
	v_mul_f32_e32 v252, v148, v148
	v_mul_f32_e32 v253, v149, v149
	v_rcp_f32_e32 v246, v246
	v_rcp_f32_e32 v247, v247
	v_rcp_f32_e32 v248, v248
	v_rcp_f32_e32 v249, v249
	v_mul_f32_e32 v250, s72, v250
	v_mul_f32_e32 v251, s72, v251
	v_mul_f32_e32 v252, s72, v252
	v_mul_f32_e32 v253, s72, v253
	v_exp_f32_e32 v250, v250
	v_exp_f32_e32 v251, v251
	v_exp_f32_e32 v252, v252
	v_exp_f32_e32 v253, v253
	v_fmamk_f32 v238, v246, 0x3f07dc22, v219
	v_fmamk_f32 v239, v247, 0x3f07dc22, v219
	v_fmamk_f32 v240, v248, 0x3f07dc22, v219
	v_fmamk_f32 v241, v249, 0x3f07dc22, v219
	v_fma_f32 v238, v246, v238, s66
	v_fma_f32 v239, v247, v239, s66
	v_fma_f32 v240, v248, v240, s66
	v_fma_f32 v241, v249, v241, s66
	v_fma_f32 v238, v246, v238, s68
	v_fma_f32 v239, v247, v239, s68
	v_fma_f32 v240, v248, v240, s68
	v_fma_f32 v241, v249, v241, s68
	v_fma_f32 v238, v246, v238, s70
	v_fma_f32 v239, v247, v239, s70
	v_fma_f32 v240, v248, v240, s70
	v_fma_f32 v241, v249, v241, s70
	v_mul_f32_e32 v238, v246, v238
	v_mul_f32_e32 v239, v247, v239
	v_mul_f32_e32 v240, v248, v240
	v_mul_f32_e32 v241, v249, v241
	v_mul_f32_e32 v238, v250, v238
	v_mul_f32_e32 v239, v251, v239
	v_mul_f32_e32 v240, v252, v240
	v_mul_f32_e32 v241, v253, v241
	v_max_f32_e32 v246, 0, v254
	v_max_f32_e32 v247, 0, v255
	v_max_f32_e32 v248, 0, v148
	v_max_f32_e32 v249, 0, v149
	v_fma_f32 v238, -|v254|, v238, v246
	v_fma_f32 v239, -|v255|, v239, v247
	v_fma_f32 v240, -|v148|, v240, v248
	v_fma_f32 v241, -|v149|, v241, v249
	v_mov_b32_dpp v112, v36 quad_perm:[0,1,2,3] row_mask:0xf bank_mask:0x8
	v_mov_b32_dpp v113, v37 quad_perm:[0,1,2,3] row_mask:0xf bank_mask:0x8
	v_mov_b32_dpp v114, v38 quad_perm:[0,1,2,3] row_mask:0xf bank_mask:0x8
	v_mov_b32_dpp v115, v39 quad_perm:[0,1,2,3] row_mask:0xf bank_mask:0x8
	v_pk_fma_f32 v[254:255], v[210:211], v[32:33], v[140:141]
	v_pk_fma_f32 v[148:149], v[212:213], v[34:35], v[142:143]
	v_fmac_f32_dpp v254, v32, v194 row_shr:1 row_mask:0xf bank_mask:0xf
	v_fmac_f32_dpp v255, v33, v195 row_shr:1 row_mask:0xf bank_mask:0xf
	v_fmac_f32_dpp v148, v34, v196 row_shr:1 row_mask:0xf bank_mask:0xf
	v_fmac_f32_dpp v149, v35, v197 row_shr:1 row_mask:0xf bank_mask:0xf
	v_fmac_f32_dpp v254, v32, v178 row_shr:2 row_mask:0xf bank_mask:0xf
	v_fmac_f32_dpp v255, v33, v179 row_shr:2 row_mask:0xf bank_mask:0xf
	v_fmac_f32_dpp v148, v34, v180 row_shr:2 row_mask:0xf bank_mask:0xf
	v_fmac_f32_dpp v149, v35, v181 row_shr:2 row_mask:0xf bank_mask:0xf
	v_fmac_f32_dpp v254, v112, v194 row_ror:1 row_mask:0xf bank_mask:0x1
; __device__ __forceinline__ unsigned cvt_pk_bf16(float lo, float hi) { unsigned r; asm volatile("v_cvt_pk_bf16_f32 %0, %1, %2" : "=v"(r) : "v"(lo), "v"(hi)); return r; }
;     __device__ __forceinline__ void operator()(const f32x4 (&acc)[2][2][4][2], const Unit& u, int wr, int wc, int fr, int fq) const {
;     ...
; #pragma unroll
;                     for (int m = 0; m < 4; ++m) {
;                         f32x4 cv;
;                         if (!samp) {
;                             const f32x4 prev = m ? v[m - 1] : hv;
; #pragma unroll
;                             for (int e = 0; e < 4; ++e) {
;                                 const int vi = __float_as_int(v[m][e]), pi = __float_as_int(prev[e]);
;                                 const int o1 = __builtin_amdgcn_mov_dpp(pi, 0x121, 0xf, 0xf, false);
;                                 const int o2 = __builtin_amdgcn_mov_dpp(pi, 0x122, 0xf, 0xf, false);
;                                 const float p1 = __int_as_float(__builtin_amdgcn_update_dpp(o1, vi, 0x111, 0xf, 0xf, false));
;                                 const float p2 = __int_as_float(__builtin_amdgcn_update_dpp(o2, vi, 0x112, 0xf, 0xf, false));
;                                 cv[e] = cb[e] + cw0[e] * p2 + cw1[e] * p1 + cw2[e] * v[m][e];
;                             }
;                         } else {
;                             const int ns = rowb + 16 * m + fr - MP;
;                             f32x4 s0 = (f32x4){0.f, 0.f, 0.f, 0.f}, s1 = s0;
;                             if (ns < NS) {
;                                 s0 = *(const f32x4*)(state + (size_t)(ns * 2 + 0) * FF2 + oc); s1 = *(const f32x4*)(state + (size_t)(ns * 2 + 1) * FF2 + oc);
;                                 *(f32x4*)(ncs + (size_t)(ns * 2 + 0) * FF2 + oc) = s1; *(f32x4*)(ncs + (size_t)(ns * 2 + 1) * FF2 + oc) = v[m];
;                             }
;                             cv = cb + cw0 * s0 + cw1 * s1 + cw2 * v[m];
;                         }
;                         if (bj == 0) cg[m] = gelu4(cv);
;                         else {
;                             const f32x4 r = cg[m] * cv;
;                             v2u w; w.x = cvt_pk_bf16(r[0], r[1]); w.y = cvt_pk_bf16(r[2], r[3]);
;                             *(v2u*)(ACT + (size_t)(rowb + 16 * m + fr) * FF + 128 * u.pn + 32 * wc + 8 * fq + 4 * n) = w;
;                         }
	v_fmac_f32_dpp v255, v113, v195 row_ror:1 row_mask:0xf bank_mask:0x1
	v_fmac_f32_dpp v148, v114, v196 row_ror:1 row_mask:0xf bank_mask:0x1
	v_fmac_f32_dpp v149, v115, v197 row_ror:1 row_mask:0xf bank_mask:0x1
	v_fmac_f32_dpp v254, v112, v178 row_ror:2 row_mask:0xf bank_mask:0x1
	v_fmac_f32_dpp v255, v113, v179 row_ror:2 row_mask:0xf bank_mask:0x1
	v_fmac_f32_dpp v148, v114, v180 row_ror:2 row_mask:0xf bank_mask:0x1
	v_fmac_f32_dpp v149, v115, v181 row_ror:2 row_mask:0xf bank_mask:0x1
	v_pk_mul_f32 v[254:255], v[238:239], v[254:255]
	v_pk_mul_f32 v[148:149], v[240:241], v[148:149]
	v_cvt_pk_bf16_f32 v242, v254, v255
	v_cvt_pk_bf16_f32 v243, v148, v149
	v_mov_b32_dpp v112, v20 quad_perm:[0,1,2,3] row_mask:0xf bank_mask:0x8
	v_mov_b32_dpp v113, v21 quad_perm:[0,1,2,3] row_mask:0xf bank_mask:0x8
	v_mov_b32_dpp v114, v22 quad_perm:[0,1,2,3] row_mask:0xf bank_mask:0x8
	v_mov_b32_dpp v115, v23 quad_perm:[0,1,2,3] row_mask:0xf bank_mask:0x8
	v_pk_fma_f32 v[254:255], v[206:207], v[16:17], v[136:137]
	v_pk_fma_f32 v[148:149], v[208:209], v[18:19], v[138:139]
	v_fmac_f32_dpp v254, v16, v190 row_shr:1 row_mask:0xf bank_mask:0xf
	v_fmac_f32_dpp v255, v17, v191 row_shr:1 row_mask:0xf bank_mask:0xf
	v_fmac_f32_dpp v148, v18, v192 row_shr:1 row_mask:0xf bank_mask:0xf
	v_fmac_f32_dpp v149, v19, v193 row_shr:1 row_mask:0xf bank_mask:0xf
	v_fmac_f32_dpp v254, v16, v174 row_shr:2 row_mask:0xf bank_mask:0xf
	v_fmac_f32_dpp v255, v17, v175 row_shr:2 row_mask:0xf bank_mask:0xf
	v_fmac_f32_dpp v148, v18, v176 row_shr:2 row_mask:0xf bank_mask:0xf
	v_fmac_f32_dpp v149, v19, v177 row_shr:2 row_mask:0xf bank_mask:0xf
	v_fmac_f32_dpp v254, v112, v190 row_ror:1 row_mask:0xf bank_mask:0x1
	v_fmac_f32_dpp v255, v113, v191 row_ror:1 row_mask:0xf bank_mask:0x1
	v_fmac_f32_dpp v148, v114, v192 row_ror:1 row_mask:0xf bank_mask:0x1
	v_fmac_f32_dpp v149, v115, v193 row_ror:1 row_mask:0xf bank_mask:0x1
	v_fmac_f32_dpp v254, v112, v174 row_ror:2 row_mask:0xf bank_mask:0x1
	v_fmac_f32_dpp v255, v113, v175 row_ror:2 row_mask:0xf bank_mask:0x1
	v_fmac_f32_dpp v148, v114, v176 row_ror:2 row_mask:0xf bank_mask:0x1
	v_fmac_f32_dpp v149, v115, v177 row_ror:2 row_mask:0xf bank_mask:0x1
	v_fma_f32 v246, |v254|, s38, 1.0
	v_fma_f32 v247, |v255|, s38, 1.0
	v_fma_f32 v248, |v148|, s38, 1.0
	v_fma_f32 v249, |v149|, s38, 1.0
	v_mul_f32_e32 v250, v254, v254
	v_mul_f32_e32 v251, v255, v255
	v_mul_f32_e32 v252, v148, v148
	v_mul_f32_e32 v253, v149, v149
	v_rcp_f32_e32 v246, v246
	v_rcp_f32_e32 v247, v247
	v_rcp_f32_e32 v248, v248
	v_rcp_f32_e32 v249, v249
	v_mul_f32_e32 v250, s72, v250
	v_mul_f32_e32 v251, s72, v251
	v_mul_f32_e32 v252, s72, v252
	v_mul_f32_e32 v253, s72, v253
	v_exp_f32_e32 v250, v250
	v_exp_f32_e32 v251, v251
	v_exp_f32_e32 v252, v252
	v_exp_f32_e32 v253, v253
	v_fmamk_f32 v238, v246, 0x3f07dc22, v219
	v_fmamk_f32 v239, v247, 0x3f07dc22, v219
	v_fmamk_f32 v240, v248, 0x3f07dc22, v219
	v_fmamk_f32 v241, v249, 0x3f07dc22, v219
	v_fma_f32 v238, v246, v238, s66
	v_fma_f32 v239, v247, v239, s66
	v_fma_f32 v240, v248, v240, s66
	v_fma_f32 v241, v249, v241, s66
	v_fma_f32 v238, v246, v238, s68
	v_fma_f32 v239, v247, v239, s68
	v_fma_f32 v240, v248, v240, s68
	v_fma_f32 v241, v249, v241, s68
	v_fma_f32 v238, v246, v238, s70
	v_fma_f32 v239, v247, v239, s70
	v_fma_f32 v240, v248, v240, s70
	v_fma_f32 v241, v249, v241, s70
	v_mul_f32_e32 v238, v246, v238
	v_mul_f32_e32 v239, v247, v239
	v_mul_f32_e32 v240, v248, v240
	v_mul_f32_e32 v241, v249, v241
	v_mul_f32_e32 v238, v250, v238
	v_mul_f32_e32 v239, v251, v239
	v_mul_f32_e32 v240, v252, v240
	v_mul_f32_e32 v241, v253, v241
	v_max_f32_e32 v246, 0, v254
	v_max_f32_e32 v247, 0, v255
	v_max_f32_e32 v248, 0, v148
	v_max_f32_e32 v249, 0, v149
	v_fma_f32 v238, -|v254|, v238, v246
	v_fma_f32 v239, -|v255|, v239, v247
	v_fma_f32 v240, -|v148|, v240, v248
	v_fma_f32 v241, -|v149|, v241, v249
	v_mov_b32_dpp v112, v4 quad_perm:[0,1,2,3] row_mask:0xf bank_mask:0x8
	v_mov_b32_dpp v113, v5 quad_perm:[0,1,2,3] row_mask:0xf bank_mask:0x8
	v_mov_b32_dpp v114, v6 quad_perm:[0,1,2,3] row_mask:0xf bank_mask:0x8
	v_mov_b32_dpp v115, v7 quad_perm:[0,1,2,3] row_mask:0xf bank_mask:0x8
	v_pk_fma_f32 v[254:255], v[128:129], v[0:1], v[144:145]
	v_pk_fma_f32 v[148:149], v[130:131], v[2:3], v[146:147]
	v_fmac_f32_dpp v254, v0, v198 row_shr:1 row_mask:0xf bank_mask:0xf
	v_fmac_f32_dpp v255, v1, v199 row_shr:1 row_mask:0xf bank_mask:0xf
	v_fmac_f32_dpp v148, v2, v200 row_shr:1 row_mask:0xf bank_mask:0xf
	v_fmac_f32_dpp v149, v3, v201 row_shr:1 row_mask:0xf bank_mask:0xf
	v_fmac_f32_dpp v254, v0, v182 row_shr:2 row_mask:0xf bank_mask:0xf
	v_fmac_f32_dpp v255, v1, v183 row_shr:2 row_mask:0xf bank_mask:0xf
	v_fmac_f32_dpp v148, v2, v184 row_shr:2 row_mask:0xf bank_mask:0xf
	v_fmac_f32_dpp v149, v3, v185 row_shr:2 row_mask:0xf bank_mask:0xf
	v_fmac_f32_dpp v254, v112, v198 row_ror:1 row_mask:0xf bank_mask:0x1
	v_fmac_f32_dpp v255, v113, v199 row_ror:1 row_mask:0xf bank_mask:0x1
	v_fmac_f32_dpp v148, v114, v200 row_ror:1 row_mask:0xf bank_mask:0x1
	v_fmac_f32_dpp v149, v115, v201 row_ror:1 row_mask:0xf bank_mask:0x1
	v_fmac_f32_dpp v254, v112, v182 row_ror:2 row_mask:0xf bank_mask:0x1
	v_fmac_f32_dpp v255, v113, v183 row_ror:2 row_mask:0xf bank_mask:0x1
	v_fmac_f32_dpp v148, v114, v184 row_ror:2 row_mask:0xf bank_mask:0x1
	v_fmac_f32_dpp v149, v115, v185 row_ror:2 row_mask:0xf bank_mask:0x1
	v_pk_mul_f32 v[254:255], v[238:239], v[254:255]
	v_pk_mul_f32 v[148:149], v[240:241], v[148:149]
	v_cvt_pk_bf16_f32 v244, v254, v255
	v_cvt_pk_bf16_f32 v245, v148, v149
	s_add_u32 s56, s46, 0xdc000
	s_addc_u32 s57, s47, 0
	global_store_dwordx4 v151, v[242:245], s[56:57]
; __device__ __forceinline__ unsigned cvt_pk_bf16(float lo, float hi) { unsigned r; asm volatile("v_cvt_pk_bf16_f32 %0, %1, %2" : "=v"(r) : "v"(lo), "v"(hi)); return r; }
;     __device__ __forceinline__ void operator()(const f32x4 (&acc)[2][2][4][2], const Unit& u, int wr, int wc, int fr, int fq) const {
;     ...
; #pragma unroll
;                     for (int m = 0; m < 4; ++m) {
;                         f32x4 cv;
;                         if (!samp) {
;                             const f32x4 prev = m ? v[m - 1] : hv;
; #pragma unroll
;                             for (int e = 0; e < 4; ++e) {
;                                 const int vi = __float_as_int(v[m][e]), pi = __float_as_int(prev[e]);
;                                 const int o1 = __builtin_amdgcn_mov_dpp(pi, 0x121, 0xf, 0xf, false);
;                                 const int o2 = __builtin_amdgcn_mov_dpp(pi, 0x122, 0xf, 0xf, false);
;                                 const float p1 = __int_as_float(__builtin_amdgcn_update_dpp(o1, vi, 0x111, 0xf, 0xf, false));
;                                 const float p2 = __int_as_float(__builtin_amdgcn_update_dpp(o2, vi, 0x112, 0xf, 0xf, false));
;                                 cv[e] = cb[e] + cw0[e] * p2 + cw1[e] * p1 + cw2[e] * v[m][e];
;                             }
;                         } else {
;                             const int ns = rowb + 16 * m + fr - MP;
;                             f32x4 s0 = (f32x4){0.f, 0.f, 0.f, 0.f}, s1 = s0;
;                             if (ns < NS) {
;                                 s0 = *(const f32x4*)(state + (size_t)(ns * 2 + 0) * FF2 + oc); s1 = *(const f32x4*)(state + (size_t)(ns * 2 + 1) * FF2 + oc);
;                                 *(f32x4*)(ncs + (size_t)(ns * 2 + 0) * FF2 + oc) = s1; *(f32x4*)(ncs + (size_t)(ns * 2 + 1) * FF2 + oc) = v[m];
;                             }
;                             cv = cb + cw0 * s0 + cw1 * s1 + cw2 * v[m];
;                         }
;                         if (bj == 0) cg[m] = gelu4(cv);
;                         else {
;                             const f32x4 r = cg[m] * cv;
;                             v2u w; w.x = cvt_pk_bf16(r[0], r[1]); w.y = cvt_pk_bf16(r[2], r[3]);
;                             *(v2u*)(ACT + (size_t)(rowb + 16 * m + fr) * FF + 128 * u.pn + 32 * wc + 8 * fq + 4 * n) = w;
;                         }
	v_mov_b32_dpp v112, v60 quad_perm:[0,1,2,3] row_mask:0xf bank_mask:0x8
	v_mov_b32_dpp v113, v61 quad_perm:[0,1,2,3] row_mask:0xf bank_mask:0x8
	v_mov_b32_dpp v114, v62 quad_perm:[0,1,2,3] row_mask:0xf bank_mask:0x8
	v_mov_b32_dpp v115, v63 quad_perm:[0,1,2,3] row_mask:0xf bank_mask:0x8
	v_pk_fma_f32 v[254:255], v[202:203], v[52:53], v[132:133]
	v_pk_fma_f32 v[148:149], v[204:205], v[54:55], v[134:135]
	v_fmac_f32_dpp v254, v52, v186 row_shr:1 row_mask:0xf bank_mask:0xf
	v_fmac_f32_dpp v255, v53, v187 row_shr:1 row_mask:0xf bank_mask:0xf
	v_fmac_f32_dpp v148, v54, v188 row_shr:1 row_mask:0xf bank_mask:0xf
	v_fmac_f32_dpp v149, v55, v189 row_shr:1 row_mask:0xf bank_mask:0xf
	v_fmac_f32_dpp v254, v52, v170 row_shr:2 row_mask:0xf bank_mask:0xf
	v_fmac_f32_dpp v255, v53, v171 row_shr:2 row_mask:0xf bank_mask:0xf
	v_fmac_f32_dpp v148, v54, v172 row_shr:2 row_mask:0xf bank_mask:0xf
	v_fmac_f32_dpp v149, v55, v173 row_shr:2 row_mask:0xf bank_mask:0xf
	v_fmac_f32_dpp v254, v112, v186 row_ror:1 row_mask:0xf bank_mask:0x1
	v_fmac_f32_dpp v255, v113, v187 row_ror:1 row_mask:0xf bank_mask:0x1
	v_fmac_f32_dpp v148, v114, v188 row_ror:1 row_mask:0xf bank_mask:0x1
	v_fmac_f32_dpp v149, v115, v189 row_ror:1 row_mask:0xf bank_mask:0x1
	v_fmac_f32_dpp v254, v112, v170 row_ror:2 row_mask:0xf bank_mask:0x1
	v_fmac_f32_dpp v255, v113, v171 row_ror:2 row_mask:0xf bank_mask:0x1
	v_fmac_f32_dpp v148, v114, v172 row_ror:2 row_mask:0xf bank_mask:0x1
	v_fmac_f32_dpp v149, v115, v173 row_ror:2 row_mask:0xf bank_mask:0x1
	v_fma_f32 v246, |v254|, s38, 1.0
	v_fma_f32 v247, |v255|, s38, 1.0
	v_fma_f32 v248, |v148|, s38, 1.0
	v_fma_f32 v249, |v149|, s38, 1.0
	v_mul_f32_e32 v250, v254, v254
	v_mul_f32_e32 v251, v255, v255
	v_mul_f32_e32 v252, v148, v148
	v_mul_f32_e32 v253, v149, v149
	v_rcp_f32_e32 v246, v246
	v_rcp_f32_e32 v247, v247
	v_rcp_f32_e32 v248, v248
	v_rcp_f32_e32 v249, v249
	v_mul_f32_e32 v250, s72, v250
	v_mul_f32_e32 v251, s72, v251
	v_mul_f32_e32 v252, s72, v252
	v_mul_f32_e32 v253, s72, v253
	v_exp_f32_e32 v250, v250
	v_exp_f32_e32 v251, v251
	v_exp_f32_e32 v252, v252
	v_exp_f32_e32 v253, v253
	v_fmamk_f32 v238, v246, 0x3f07dc22, v219
	v_fmamk_f32 v239, v247, 0x3f07dc22, v219
	v_fmamk_f32 v240, v248, 0x3f07dc22, v219
	v_fmamk_f32 v241, v249, 0x3f07dc22, v219
	v_fma_f32 v238, v246, v238, s66
	v_fma_f32 v239, v247, v239, s66
	v_fma_f32 v240, v248, v240, s66
	v_fma_f32 v241, v249, v241, s66
	v_fma_f32 v238, v246, v238, s68
	v_fma_f32 v239, v247, v239, s68
	v_fma_f32 v240, v248, v240, s68
	v_fma_f32 v241, v249, v241, s68
	v_fma_f32 v238, v246, v238, s70
	v_fma_f32 v239, v247, v239, s70
	v_fma_f32 v240, v248, v240, s70
	v_fma_f32 v241, v249, v241, s70
	v_mul_f32_e32 v238, v246, v238
	v_mul_f32_e32 v239, v247, v239
	v_mul_f32_e32 v240, v248, v240
	v_mul_f32_e32 v241, v249, v241
	v_mul_f32_e32 v238, v250, v238
	v_mul_f32_e32 v239, v251, v239
	v_mul_f32_e32 v240, v252, v240
	v_mul_f32_e32 v241, v253, v241
	v_max_f32_e32 v246, 0, v254
	v_max_f32_e32 v247, 0, v255
	v_max_f32_e32 v248, 0, v148
	v_max_f32_e32 v249, 0, v149
	v_fma_f32 v238, -|v254|, v238, v246
	v_fma_f32 v239, -|v255|, v239, v247
	v_fma_f32 v240, -|v148|, v240, v248
	v_fma_f32 v241, -|v149|, v241, v249
	v_mov_b32_dpp v112, v44 quad_perm:[0,1,2,3] row_mask:0xf bank_mask:0x8
	v_mov_b32_dpp v113, v45 quad_perm:[0,1,2,3] row_mask:0xf bank_mask:0x8
	v_mov_b32_dpp v114, v46 quad_perm:[0,1,2,3] row_mask:0xf bank_mask:0x8
	v_mov_b32_dpp v115, v47 quad_perm:[0,1,2,3] row_mask:0xf bank_mask:0x8
	v_pk_fma_f32 v[254:255], v[210:211], v[36:37], v[140:141]
	v_pk_fma_f32 v[148:149], v[212:213], v[38:39], v[142:143]
	v_fmac_f32_dpp v254, v36, v194 row_shr:1 row_mask:0xf bank_mask:0xf
	v_fmac_f32_dpp v255, v37, v195 row_shr:1 row_mask:0xf bank_mask:0xf
	v_fmac_f32_dpp v148, v38, v196 row_shr:1 row_mask:0xf bank_mask:0xf
	v_fmac_f32_dpp v149, v39, v197 row_shr:1 row_mask:0xf bank_mask:0xf
	v_fmac_f32_dpp v254, v36, v178 row_shr:2 row_mask:0xf bank_mask:0xf
	v_fmac_f32_dpp v255, v37, v179 row_shr:2 row_mask:0xf bank_mask:0xf
	v_fmac_f32_dpp v148, v38, v180 row_shr:2 row_mask:0xf bank_mask:0xf
	v_fmac_f32_dpp v149, v39, v181 row_shr:2 row_mask:0xf bank_mask:0xf
	v_fmac_f32_dpp v254, v112, v194 row_ror:1 row_mask:0xf bank_mask:0x1
	v_fmac_f32_dpp v255, v113, v195 row_ror:1 row_mask:0xf bank_mask:0x1
	v_fmac_f32_dpp v148, v114, v196 row_ror:1 row_mask:0xf bank_mask:0x1
	v_fmac_f32_dpp v149, v115, v197 row_ror:1 row_mask:0xf bank_mask:0x1
	v_fmac_f32_dpp v254, v112, v178 row_ror:2 row_mask:0xf bank_mask:0x1
	v_fmac_f32_dpp v255, v113, v179 row_ror:2 row_mask:0xf bank_mask:0x1
	v_fmac_f32_dpp v148, v114, v180 row_ror:2 row_mask:0xf bank_mask:0x1
	v_fmac_f32_dpp v149, v115, v181 row_ror:2 row_mask:0xf bank_mask:0x1
	v_pk_mul_f32 v[254:255], v[238:239], v[254:255]
	v_pk_mul_f32 v[148:149], v[240:241], v[148:149]
	v_cvt_pk_bf16_f32 v242, v254, v255
	v_cvt_pk_bf16_f32 v243, v148, v149
	v_mov_b32_dpp v112, v28 quad_perm:[0,1,2,3] row_mask:0xf bank_mask:0x8
	v_mov_b32_dpp v113, v29 quad_perm:[0,1,2,3] row_mask:0xf bank_mask:0x8
;     __device__ __forceinline__ void operator()(const f32x4 (&acc)[2][2][4][2], const Unit& u, int wr, int wc, int fr, int fq) const {
;     ...
;         if (!halo_ok) {
;             if (threadIdx.x < 64) { unsigned sp = 0;
;     ...
; #pragma unroll
;                     for (int m = 0; m < 4; ++m) {
;                         f32x4 cv;
;                         if (!samp) {
;                             const f32x4 prev = m ? v[m - 1] : hv;
; #pragma unroll
;                             for (int e = 0; e < 4; ++e) {
;                                 const int vi = __float_as_int(v[m][e]), pi = __float_as_int(prev[e]);
;                                 const int o1 = __builtin_amdgcn_mov_dpp(pi, 0x121, 0xf, 0xf, false);
;                                 const int o2 = __builtin_amdgcn_mov_dpp(pi, 0x122, 0xf, 0xf, false);
;                                 const float p1 = __int_as_float(__builtin_amdgcn_update_dpp(o1, vi, 0x111, 0xf, 0xf, false));
;                                 const float p2 = __int_as_float(__builtin_amdgcn_update_dpp(o2, vi, 0x112, 0xf, 0xf, false));
;                                 cv[e] = cb[e] + cw0[e] * p2 + cw1[e] * p1 + cw2[e] * v[m][e];
;                             }
;                         } else {
;                             const int ns = rowb + 16 * m + fr - MP;
;                             f32x4 s0 = (f32x4){0.f, 0.f, 0.f, 0.f}, s1 = s0;
;                             if (ns < NS) {
;                                 s0 = *(const f32x4*)(state + (size_t)(ns * 2 + 0) * FF2 + oc); s1 = *(const f32x4*)(state + (size_t)(ns * 2 + 1) * FF2 + oc);
;                                 *(f32x4*)(ncs + (size_t)(ns * 2 + 0) * FF2 + oc) = s1; *(f32x4*)(ncs + (size_t)(ns * 2 + 1) * FF2 + oc) = v[m];
;                             }
;                             cv = cb + cw0 * s0 + cw1 * s1 + cw2 * v[m];
;                         }
;                         if (bj == 0) cg[m] = gelu4(cv);
;                         else {
;                             const f32x4 r = cg[m] * cv;
;                             v2u w; w.x = cvt_pk_bf16(r[0], r[1]); w.y = cvt_pk_bf16(r[2], r[3]);
;                             *(v2u*)(ACT + (size_t)(rowb + 16 * m + fr) * FF + 128 * u.pn + 32 * wc + 8 * fq + 4 * n) = w;
;                         }
	v_mov_b32_dpp v114, v30 quad_perm:[0,1,2,3] row_mask:0xf bank_mask:0x8
	v_mov_b32_dpp v115, v31 quad_perm:[0,1,2,3] row_mask:0xf bank_mask:0x8
	v_pk_fma_f32 v[254:255], v[206:207], v[20:21], v[136:137]
	v_pk_fma_f32 v[148:149], v[208:209], v[22:23], v[138:139]
	v_fmac_f32_dpp v254, v20, v190 row_shr:1 row_mask:0xf bank_mask:0xf
	v_fmac_f32_dpp v255, v21, v191 row_shr:1 row_mask:0xf bank_mask:0xf
	v_fmac_f32_dpp v148, v22, v192 row_shr:1 row_mask:0xf bank_mask:0xf
	v_fmac_f32_dpp v149, v23, v193 row_shr:1 row_mask:0xf bank_mask:0xf
	v_fmac_f32_dpp v254, v20, v174 row_shr:2 row_mask:0xf bank_mask:0xf
	v_fmac_f32_dpp v255, v21, v175 row_shr:2 row_mask:0xf bank_mask:0xf
	v_fmac_f32_dpp v148, v22, v176 row_shr:2 row_mask:0xf bank_mask:0xf
	v_fmac_f32_dpp v149, v23, v177 row_shr:2 row_mask:0xf bank_mask:0xf
	v_fmac_f32_dpp v254, v112, v190 row_ror:1 row_mask:0xf bank_mask:0x1
	v_fmac_f32_dpp v255, v113, v191 row_ror:1 row_mask:0xf bank_mask:0x1
	v_fmac_f32_dpp v148, v114, v192 row_ror:1 row_mask:0xf bank_mask:0x1
	v_fmac_f32_dpp v149, v115, v193 row_ror:1 row_mask:0xf bank_mask:0x1
	v_fmac_f32_dpp v254, v112, v174 row_ror:2 row_mask:0xf bank_mask:0x1
	v_fmac_f32_dpp v255, v113, v175 row_ror:2 row_mask:0xf bank_mask:0x1
	v_fmac_f32_dpp v148, v114, v176 row_ror:2 row_mask:0xf bank_mask:0x1
	v_fmac_f32_dpp v149, v115, v177 row_ror:2 row_mask:0xf bank_mask:0x1
	v_fma_f32 v246, |v254|, s38, 1.0
	v_fma_f32 v247, |v255|, s38, 1.0
	v_fma_f32 v248, |v148|, s38, 1.0
	v_fma_f32 v249, |v149|, s38, 1.0
	v_mul_f32_e32 v250, v254, v254
	v_mul_f32_e32 v251, v255, v255
	v_mul_f32_e32 v252, v148, v148
	v_mul_f32_e32 v253, v149, v149
	v_rcp_f32_e32 v246, v246
	v_rcp_f32_e32 v247, v247
	v_rcp_f32_e32 v248, v248
	v_rcp_f32_e32 v249, v249
	v_mul_f32_e32 v250, s72, v250
	v_mul_f32_e32 v251, s72, v251
	v_mul_f32_e32 v252, s72, v252
	v_mul_f32_e32 v253, s72, v253
	v_exp_f32_e32 v250, v250
	v_exp_f32_e32 v251, v251
	v_exp_f32_e32 v252, v252
	v_exp_f32_e32 v253, v253
	v_fmamk_f32 v238, v246, 0x3f07dc22, v219
	v_fmamk_f32 v239, v247, 0x3f07dc22, v219
	v_fmamk_f32 v240, v248, 0x3f07dc22, v219
	v_fmamk_f32 v241, v249, 0x3f07dc22, v219
	v_fma_f32 v238, v246, v238, s66
	v_fma_f32 v239, v247, v239, s66
	v_fma_f32 v240, v248, v240, s66
	v_fma_f32 v241, v249, v241, s66
	v_fma_f32 v238, v246, v238, s68
	v_fma_f32 v239, v247, v239, s68
	v_fma_f32 v240, v248, v240, s68
	v_fma_f32 v241, v249, v241, s68
	v_fma_f32 v238, v246, v238, s70
	v_fma_f32 v239, v247, v239, s70
	v_fma_f32 v240, v248, v240, s70
	v_fma_f32 v241, v249, v241, s70
	v_mul_f32_e32 v238, v246, v238
	v_mul_f32_e32 v239, v247, v239
	v_mul_f32_e32 v240, v248, v240
	v_mul_f32_e32 v241, v249, v241
	v_mul_f32_e32 v238, v250, v238
	v_mul_f32_e32 v239, v251, v239
	v_mul_f32_e32 v240, v252, v240
	v_mul_f32_e32 v241, v253, v241
	v_max_f32_e32 v246, 0, v254
	v_max_f32_e32 v247, 0, v255
	v_max_f32_e32 v248, 0, v148
	v_max_f32_e32 v249, 0, v149
	v_fma_f32 v238, -|v254|, v238, v246
	v_fma_f32 v239, -|v255|, v239, v247
	v_fma_f32 v240, -|v148|, v240, v248
	v_fma_f32 v241, -|v149|, v241, v249
	v_mov_b32_dpp v112, v12 quad_perm:[0,1,2,3] row_mask:0xf bank_mask:0x8
	v_mov_b32_dpp v113, v13 quad_perm:[0,1,2,3] row_mask:0xf bank_mask:0x8
	v_mov_b32_dpp v114, v14 quad_perm:[0,1,2,3] row_mask:0xf bank_mask:0x8
	v_mov_b32_dpp v115, v15 quad_perm:[0,1,2,3] row_mask:0xf bank_mask:0x8
	v_pk_fma_f32 v[254:255], v[128:129], v[4:5], v[144:145]
	v_pk_fma_f32 v[148:149], v[130:131], v[6:7], v[146:147]
	v_fmac_f32_dpp v254, v4, v198 row_shr:1 row_mask:0xf bank_mask:0xf
	v_fmac_f32_dpp v255, v5, v199 row_shr:1 row_mask:0xf bank_mask:0xf
	v_fmac_f32_dpp v148, v6, v200 row_shr:1 row_mask:0xf bank_mask:0xf
	v_fmac_f32_dpp v149, v7, v201 row_shr:1 row_mask:0xf bank_mask:0xf
	v_fmac_f32_dpp v254, v4, v182 row_shr:2 row_mask:0xf bank_mask:0xf
	v_fmac_f32_dpp v255, v5, v183 row_shr:2 row_mask:0xf bank_mask:0xf
	v_fmac_f32_dpp v148, v6, v184 row_shr:2 row_mask:0xf bank_mask:0xf
	v_fmac_f32_dpp v149, v7, v185 row_shr:2 row_mask:0xf bank_mask:0xf
	v_fmac_f32_dpp v254, v112, v198 row_ror:1 row_mask:0xf bank_mask:0x1
	v_fmac_f32_dpp v255, v113, v199 row_ror:1 row_mask:0xf bank_mask:0x1
	v_fmac_f32_dpp v148, v114, v200 row_ror:1 row_mask:0xf bank_mask:0x1
	v_fmac_f32_dpp v149, v115, v201 row_ror:1 row_mask:0xf bank_mask:0x1
	v_fmac_f32_dpp v254, v112, v182 row_ror:2 row_mask:0xf bank_mask:0x1
	v_fmac_f32_dpp v255, v113, v183 row_ror:2 row_mask:0xf bank_mask:0x1
	v_fmac_f32_dpp v148, v114, v184 row_ror:2 row_mask:0xf bank_mask:0x1
	v_fmac_f32_dpp v149, v115, v185 row_ror:2 row_mask:0xf bank_mask:0x1
	v_pk_mul_f32 v[254:255], v[238:239], v[254:255]
	v_pk_mul_f32 v[148:149], v[240:241], v[148:149]
	v_cvt_pk_bf16_f32 v244, v254, v255
	v_cvt_pk_bf16_f32 v245, v148, v149
	s_add_u32 s56, s46, 0xc6000
	s_addc_u32 s57, s47, 0
	global_store_dwordx4 v151, v[242:245], s[56:57]
	s_and_b64 vcc, exec, s[86:87]
	s_cbranch_vccz .Lfe_h0b
	s_and_saveexec_b64 s[14:15], s[8:9]
	s_cbranch_execz .Lfe_hw3
	s_mov_b32 s13, 0x100001
	s_branch .Lfe_hw1

;     __device__ __forceinline__ void operator()(const f32x4 (&acc)[2][2][4][2], const Unit& u, int wr, int wc, int fr, int fq) const {
;     ...
;             if (threadIdx.x < 64) { unsigned sp = 0;
;                 while ((unsigned)__builtin_amdgcn_readfirstlane(__hip_atomic_load(halo_ctr, __ATOMIC_RELAXED, __HIP_MEMORY_SCOPE_AGENT)) < halo_need) { __builtin_amdgcn_s_sleep(8); if (++sp > (1u << 20)) break; }
;                 __builtin_amdgcn_fence(__ATOMIC_ACQUIRE, "agent"); asm volatile("s_waitcnt vmcnt(0)" ::: "memory"); }
.Lfe_hw1:
	global_load_dword v247, v169, s[40:41] sc1
	s_mov_b64 s[84:85], -1
	s_waitcnt vmcnt(0)
	v_readfirstlane_b32 s48, v247
	s_cmp_gt_u32 s48, 43
	s_cbranch_scc1 .Lfe_hw0
	s_add_i32 s13, s13, -1
	s_cmp_eq_u32 s13, 0
	s_cselect_b64 s[84:85], -1, 0
	s_sleep 8
	s_branch .Lfe_hw0

;     __device__ __forceinline__ void operator()(const f32x4 (&acc)[2][2][4][2], const Unit& u, int wr, int wc, int fr, int fq) const {
;     ...
;         if (!halo_ok) {
;             if (threadIdx.x < 64) { unsigned sp = 0;
;                 while ((unsigned)__builtin_amdgcn_readfirstlane(__hip_atomic_load(halo_ctr, __ATOMIC_RELAXED, __HIP_MEMORY_SCOPE_AGENT)) < halo_need) { __builtin_amdgcn_s_sleep(8); if (++sp > (1u << 20)) break; }
;                 __builtin_amdgcn_fence(__ATOMIC_ACQUIRE, "agent"); asm volatile("s_waitcnt vmcnt(0)" ::: "memory"); }
;             asm volatile("" ::: "memory"); __builtin_amdgcn_s_barrier(); asm volatile("" ::: "memory");
;             halo_ok = 1;
;         }
;         const bool samp = (u.pm == 64);
; #pragma unroll
;         for (int ai = 0; ai < 2; ++ai) {
;             const int rowb = u.pm * 256 + ai * 128 + wr * 64;
;             const int blk = 4 * u.pm + 2 * ai + wr;
;             float rs[4];
; #pragma unroll
;             for (int m = 0; m < 4; ++m) rs[m] = rsqrtf(SS[rowb + 16 * m + fr] * (1.0f / D) + EPS);
; #pragma unroll
;             for (int n = 0; n < 2; ++n) {
;                 f32x4 cg[4];
; #pragma unroll
;                 for (int bj = 0; bj < 2; ++bj) {
;                     const int oc = (bj ? FF : 0) + 128 * u.pn + 32 * wc + 8 * fq + 4 * n;
;                     const int cgc = 256 * u.pn + 128 * bj + 32 * wc + 8 * fq + 4 * n;
;                     const f32x4 cw0 = *(const f32x4*)(convw + oc), cw1 = *(const f32x4*)(convw + FF2 + oc), cw2 = *(const f32x4*)(convw + 2 * FF2 + oc), cb = *(const f32x4*)(convb + oc);
;                     f32x4 v[4];
; #pragma unroll
;                     for (int m = 0; m < 4; ++m) v[m] = acc[ai][bj][m][n] * rs[m];
;                     f32x4 hv = (f32x4){0.f, 0.f, 0.f, 0.f};
;                     if (!samp) {
;                         if ((blk & 31) != 0 && fr >= 14) hv = *(const f32x4*)(HALO + (size_t)(2 * blk + fr - 14) * FF2 + cgc);
.Lfe_hw3:
	s_or_b64 exec, exec, s[14:15]
	s_barrier
	v_add_u32_e32 v246, 0x16000, v150
	s_mov_b64 s[14:15], exec
	s_mov_b64 exec, s[10:11]
	global_load_dwordx4 v[116:119], v246, s[44:45]
	global_load_dwordx4 v[84:87], v246, s[44:45] offset:16
	global_load_dwordx4 v[100:103], v246, s[44:45] offset:512
	global_load_dwordx4 v[68:71], v246, s[44:45] offset:528
	s_mov_b64 exec, s[14:15]
	s_and_b64 vcc, exec, s[92:93]
	s_cbranch_vccz .Lfe_h0c
	s_mov_b64 s[14:15], exec
	s_mov_b64 exec, s[10:11]
	global_load_dwordx4 v[220:223], v150, s[44:45]
	global_load_dwordx4 v[224:227], v150, s[44:45] offset:16
	global_load_dwordx4 v[228:231], v150, s[44:45] offset:512
	global_load_dwordx4 v[232:235], v150, s[44:45] offset:528
	s_mov_b64 exec, s[14:15]

;     __device__ __forceinline__ void operator()(const f32x4 (&acc)[2][2][4][2], const Unit& u, int wr, int wc, int fr, int fq) const {
;     ...
;                         if ((blk & 31) != 0 && fr >= 14) hv = *(const f32x4*)(HALO + (size_t)(2 * blk + fr - 14) * FF2 + cgc);
;                         if ((u.pm & 7) == 7 && ai == 1 && wr == 1 && fr >= 14) *(f32x4*)(ncp + (size_t)((u.pm >> 3) * 2 + (fr - 14)) * FF2 + oc) = v[3];
;                     }
; #pragma unroll
;                     for (int m = 0; m < 4; ++m) {
;                         f32x4 cv;
;                         if (!samp) {
;                             const f32x4 prev = m ? v[m - 1] : hv;
; #pragma unroll
;                             for (int e = 0; e < 4; ++e) {
;                                 const int vi = __float_as_int(v[m][e]), pi = __float_as_int(prev[e]);
;                                 const int o1 = __builtin_amdgcn_mov_dpp(pi, 0x121, 0xf, 0xf, false);
;                                 const int o2 = __builtin_amdgcn_mov_dpp(pi, 0x122, 0xf, 0xf, false);
;                                 const float p1 = __int_as_float(__builtin_amdgcn_update_dpp(o1, vi, 0x111, 0xf, 0xf, false));
;                                 const float p2 = __int_as_float(__builtin_amdgcn_update_dpp(o2, vi, 0x112, 0xf, 0xf, false));
;                                 cv[e] = cb[e] + cw0[e] * p2 + cw1[e] * p1 + cw2[e] * v[m][e];
;                             }
;                         } else {
;                             const int ns = rowb + 16 * m + fr - MP;
;                             f32x4 s0 = (f32x4){0.f, 0.f, 0.f, 0.f}, s1 = s0;
;                             if (ns < NS) {
;                                 s0 = *(const f32x4*)(state + (size_t)(ns * 2 + 0) * FF2 + oc); s1 = *(const f32x4*)(state + (size_t)(ns * 2 + 1) * FF2 + oc);
;                                 *(f32x4*)(ncs + (size_t)(ns * 2 + 0) * FF2 + oc) = s1; *(f32x4*)(ncs + (size_t)(ns * 2 + 1) * FF2 + oc) = v[m];
;                             }
;                             cv = cb + cw0 * s0 + cw1 * s1 + cw2 * v[m];
;                         }
;                         if (bj == 0) cg[m] = gelu4(cv);
;                         else {
;                             const f32x4 r = cg[m] * cv;
;                             v2u w; w.x = cvt_pk_bf16(r[0], r[1]); w.y = cvt_pk_bf16(r[2], r[3]);
.Lfe_h0b:
	s_waitcnt vmcnt(4)
	v_pk_fma_f32 v[254:255], v[202:203], v[124:125], v[132:133]
	v_pk_fma_f32 v[148:149], v[204:205], v[126:127], v[134:135]
	v_fmac_f32_dpp v254, v124, v186 row_shr:1 row_mask:0xf bank_mask:0xf
	v_fmac_f32_dpp v255, v125, v187 row_shr:1 row_mask:0xf bank_mask:0xf
	v_fmac_f32_dpp v148, v126, v188 row_shr:1 row_mask:0xf bank_mask:0xf
	v_fmac_f32_dpp v149, v127, v189 row_shr:1 row_mask:0xf bank_mask:0xf
	v_fmac_f32_dpp v254, v124, v170 row_shr:2 row_mask:0xf bank_mask:0xf
	v_fmac_f32_dpp v255, v125, v171 row_shr:2 row_mask:0xf bank_mask:0xf
	v_fmac_f32_dpp v148, v126, v172 row_shr:2 row_mask:0xf bank_mask:0xf
	v_fmac_f32_dpp v149, v127, v173 row_shr:2 row_mask:0xf bank_mask:0xf
	v_fmac_f32_dpp v254, v220, v186 row_ror:1 row_mask:0xf bank_mask:0x1
	v_fmac_f32_dpp v255, v221, v187 row_ror:1 row_mask:0xf bank_mask:0x1
	v_fmac_f32_dpp v148, v222, v188 row_ror:1 row_mask:0xf bank_mask:0x1
	v_fmac_f32_dpp v149, v223, v189 row_ror:1 row_mask:0xf bank_mask:0x1
	v_fmac_f32_dpp v254, v220, v170 row_ror:2 row_mask:0xf bank_mask:0x1
	v_fmac_f32_dpp v255, v221, v171 row_ror:2 row_mask:0xf bank_mask:0x1
	v_fmac_f32_dpp v148, v222, v172 row_ror:2 row_mask:0xf bank_mask:0x1
	v_fmac_f32_dpp v149, v223, v173 row_ror:2 row_mask:0xf bank_mask:0x1
	v_fma_f32 v246, |v254|, s38, 1.0
	v_fma_f32 v247, |v255|, s38, 1.0
	v_fma_f32 v248, |v148|, s38, 1.0
	v_fma_f32 v249, |v149|, s38, 1.0
	v_mul_f32_e32 v250, v254, v254
	v_mul_f32_e32 v251, v255, v255
	v_mul_f32_e32 v252, v148, v148
	v_mul_f32_e32 v253, v149, v149
	v_rcp_f32_e32 v246, v246
	v_rcp_f32_e32 v247, v247
	v_rcp_f32_e32 v248, v248
	v_rcp_f32_e32 v249, v249
	v_mul_f32_e32 v250, s72, v250
	v_mul_f32_e32 v251, s72, v251
	v_mul_f32_e32 v252, s72, v252
	v_mul_f32_e32 v253, s72, v253
	v_exp_f32_e32 v250, v250
	v_exp_f32_e32 v251, v251
	v_exp_f32_e32 v252, v252
	v_exp_f32_e32 v253, v253
	v_fmamk_f32 v238, v246, 0x3f07dc22, v219
	v_fmamk_f32 v239, v247, 0x3f07dc22, v219
	v_fmamk_f32 v240, v248, 0x3f07dc22, v219
	v_fmamk_f32 v241, v249, 0x3f07dc22, v219
	v_fma_f32 v238, v246, v238, s66
	v_fma_f32 v239, v247, v239, s66
	v_fma_f32 v240, v248, v240, s66
	v_fma_f32 v241, v249, v241, s66
	v_fma_f32 v238, v246, v238, s68
	v_fma_f32 v239, v247, v239, s68
	v_fma_f32 v240, v248, v240, s68
	v_fma_f32 v241, v249, v241, s68
	v_fma_f32 v238, v246, v238, s70
	v_fma_f32 v239, v247, v239, s70
	v_fma_f32 v240, v248, v240, s70
	v_fma_f32 v241, v249, v241, s70
	v_mul_f32_e32 v238, v246, v238
	v_mul_f32_e32 v239, v247, v239
	v_mul_f32_e32 v240, v248, v240
	v_mul_f32_e32 v241, v249, v241
	v_mul_f32_e32 v238, v250, v238
	v_mul_f32_e32 v239, v251, v239
	v_mul_f32_e32 v240, v252, v240
	v_mul_f32_e32 v241, v253, v241
	v_max_f32_e32 v246, 0, v254
	v_max_f32_e32 v247, 0, v255
	v_max_f32_e32 v248, 0, v148
	v_max_f32_e32 v249, 0, v149
	v_fma_f32 v238, -|v254|, v238, v246
	v_fma_f32 v239, -|v255|, v239, v247
	v_fma_f32 v240, -|v148|, v240, v248
	v_fma_f32 v241, -|v149|, v241, v249
	v_pk_fma_f32 v[254:255], v[210:211], v[108:109], v[140:141]
	v_pk_fma_f32 v[148:149], v[212:213], v[110:111], v[142:143]
	v_fmac_f32_dpp v254, v108, v194 row_shr:1 row_mask:0xf bank_mask:0xf
	v_fmac_f32_dpp v255, v109, v195 row_shr:1 row_mask:0xf bank_mask:0xf
	v_fmac_f32_dpp v148, v110, v196 row_shr:1 row_mask:0xf bank_mask:0xf
	v_fmac_f32_dpp v149, v111, v197 row_shr:1 row_mask:0xf bank_mask:0xf
	v_fmac_f32_dpp v254, v108, v178 row_shr:2 row_mask:0xf bank_mask:0xf
	v_fmac_f32_dpp v255, v109, v179 row_shr:2 row_mask:0xf bank_mask:0xf
	v_fmac_f32_dpp v148, v110, v180 row_shr:2 row_mask:0xf bank_mask:0xf
	v_fmac_f32_dpp v149, v111, v181 row_shr:2 row_mask:0xf bank_mask:0xf
	v_fmac_f32_dpp v254, v228, v194 row_ror:1 row_mask:0xf bank_mask:0x1
	v_fmac_f32_dpp v255, v229, v195 row_ror:1 row_mask:0xf bank_mask:0x1
	v_fmac_f32_dpp v148, v230, v196 row_ror:1 row_mask:0xf bank_mask:0x1
	v_fmac_f32_dpp v149, v231, v197 row_ror:1 row_mask:0xf bank_mask:0x1
	v_fmac_f32_dpp v254, v228, v178 row_ror:2 row_mask:0xf bank_mask:0x1
	v_fmac_f32_dpp v255, v229, v179 row_ror:2 row_mask:0xf bank_mask:0x1
	v_fmac_f32_dpp v148, v230, v180 row_ror:2 row_mask:0xf bank_mask:0x1
	v_fmac_f32_dpp v149, v231, v181 row_ror:2 row_mask:0xf bank_mask:0x1
	v_pk_mul_f32 v[254:255], v[238:239], v[254:255]
	v_pk_mul_f32 v[148:149], v[240:241], v[148:149]
	v_cvt_pk_bf16_f32 v242, v254, v255
	v_cvt_pk_bf16_f32 v243, v148, v149
	v_pk_fma_f32 v[254:255], v[206:207], v[92:93], v[136:137]
	v_pk_fma_f32 v[148:149], v[208:209], v[94:95], v[138:139]
	v_fmac_f32_dpp v254, v92, v190 row_shr:1 row_mask:0xf bank_mask:0xf
	v_fmac_f32_dpp v255, v93, v191 row_shr:1 row_mask:0xf bank_mask:0xf
	v_fmac_f32_dpp v148, v94, v192 row_shr:1 row_mask:0xf bank_mask:0xf
	v_fmac_f32_dpp v149, v95, v193 row_shr:1 row_mask:0xf bank_mask:0xf
	v_fmac_f32_dpp v254, v92, v174 row_shr:2 row_mask:0xf bank_mask:0xf
	v_fmac_f32_dpp v255, v93, v175 row_shr:2 row_mask:0xf bank_mask:0xf
	v_fmac_f32_dpp v148, v94, v176 row_shr:2 row_mask:0xf bank_mask:0xf
	v_fmac_f32_dpp v149, v95, v177 row_shr:2 row_mask:0xf bank_mask:0xf
	v_fmac_f32_dpp v254, v224, v190 row_ror:1 row_mask:0xf bank_mask:0x1
	v_fmac_f32_dpp v255, v225, v191 row_ror:1 row_mask:0xf bank_mask:0x1
	v_fmac_f32_dpp v148, v226, v192 row_ror:1 row_mask:0xf bank_mask:0x1
	v_fmac_f32_dpp v149, v227, v193 row_ror:1 row_mask:0xf bank_mask:0x1
	v_fmac_f32_dpp v254, v224, v174 row_ror:2 row_mask:0xf bank_mask:0x1
	v_fmac_f32_dpp v255, v225, v175 row_ror:2 row_mask:0xf bank_mask:0x1
	v_fmac_f32_dpp v148, v226, v176 row_ror:2 row_mask:0xf bank_mask:0x1
	v_fmac_f32_dpp v149, v227, v177 row_ror:2 row_mask:0xf bank_mask:0x1
	v_fma_f32 v246, |v254|, s38, 1.0
;     __device__ __forceinline__ void operator()(const f32x4 (&acc)[2][2][4][2], const Unit& u, int wr, int wc, int fr, int fq) const {
;     ...
;                         if ((blk & 31) != 0 && fr >= 14) hv = *(const f32x4*)(HALO + (size_t)(2 * blk + fr - 14) * FF2 + cgc);
;                         if ((u.pm & 7) == 7 && ai == 1 && wr == 1 && fr >= 14) *(f32x4*)(ncp + (size_t)((u.pm >> 3) * 2 + (fr - 14)) * FF2 + oc) = v[3];
;                     }
; #pragma unroll
;                     for (int m = 0; m < 4; ++m) {
;                         f32x4 cv;
;                         if (!samp) {
;                             const f32x4 prev = m ? v[m - 1] : hv;
; #pragma unroll
;                             for (int e = 0; e < 4; ++e) {
;                                 const int vi = __float_as_int(v[m][e]), pi = __float_as_int(prev[e]);
;                                 const int o1 = __builtin_amdgcn_mov_dpp(pi, 0x121, 0xf, 0xf, false);
;                                 const int o2 = __builtin_amdgcn_mov_dpp(pi, 0x122, 0xf, 0xf, false);
;                                 const float p1 = __int_as_float(__builtin_amdgcn_update_dpp(o1, vi, 0x111, 0xf, 0xf, false));
;                                 const float p2 = __int_as_float(__builtin_amdgcn_update_dpp(o2, vi, 0x112, 0xf, 0xf, false));
;                                 cv[e] = cb[e] + cw0[e] * p2 + cw1[e] * p1 + cw2[e] * v[m][e];
;                             }
;                         } else {
;                             const int ns = rowb + 16 * m + fr - MP;
;                             f32x4 s0 = (f32x4){0.f, 0.f, 0.f, 0.f}, s1 = s0;
;                             if (ns < NS) {
;                                 s0 = *(const f32x4*)(state + (size_t)(ns * 2 + 0) * FF2 + oc); s1 = *(const f32x4*)(state + (size_t)(ns * 2 + 1) * FF2 + oc);
;                                 *(f32x4*)(ncs + (size_t)(ns * 2 + 0) * FF2 + oc) = s1; *(f32x4*)(ncs + (size_t)(ns * 2 + 1) * FF2 + oc) = v[m];
;                             }
;                             cv = cb + cw0 * s0 + cw1 * s1 + cw2 * v[m];
;                         }
;                         if (bj == 0) cg[m] = gelu4(cv);
;                         else {
;                             const f32x4 r = cg[m] * cv;
;                             v2u w; w.x = cvt_pk_bf16(r[0], r[1]); w.y = cvt_pk_bf16(r[2], r[3]);
	v_fma_f32 v247, |v255|, s38, 1.0
	v_fma_f32 v248, |v148|, s38, 1.0
	v_fma_f32 v249, |v149|, s38, 1.0
	v_mul_f32_e32 v250, v254, v254
	v_mul_f32_e32 v251, v255, v255
	v_mul_f32_e32 v252, v148, v148
	v_mul_f32_e32 v253, v149, v149
	v_rcp_f32_e32 v246, v246
	v_rcp_f32_e32 v247, v247
	v_rcp_f32_e32 v248, v248
	v_rcp_f32_e32 v249, v249
	v_mul_f32_e32 v250, s72, v250
	v_mul_f32_e32 v251, s72, v251
	v_mul_f32_e32 v252, s72, v252
	v_mul_f32_e32 v253, s72, v253
	v_exp_f32_e32 v250, v250
	v_exp_f32_e32 v251, v251
	v_exp_f32_e32 v252, v252
	v_exp_f32_e32 v253, v253
	v_fmamk_f32 v238, v246, 0x3f07dc22, v219
	v_fmamk_f32 v239, v247, 0x3f07dc22, v219
	v_fmamk_f32 v240, v248, 0x3f07dc22, v219
	v_fmamk_f32 v241, v249, 0x3f07dc22, v219
	v_fma_f32 v238, v246, v238, s66
	v_fma_f32 v239, v247, v239, s66
	v_fma_f32 v240, v248, v240, s66
	v_fma_f32 v241, v249, v241, s66
	v_fma_f32 v238, v246, v238, s68
	v_fma_f32 v239, v247, v239, s68
	v_fma_f32 v240, v248, v240, s68
	v_fma_f32 v241, v249, v241, s68
	v_fma_f32 v238, v246, v238, s70
	v_fma_f32 v239, v247, v239, s70
	v_fma_f32 v240, v248, v240, s70
	v_fma_f32 v241, v249, v241, s70
	v_mul_f32_e32 v238, v246, v238
	v_mul_f32_e32 v239, v247, v239
	v_mul_f32_e32 v240, v248, v240
	v_mul_f32_e32 v241, v249, v241
	v_mul_f32_e32 v238, v250, v238
	v_mul_f32_e32 v239, v251, v239
	v_mul_f32_e32 v240, v252, v240
	v_mul_f32_e32 v241, v253, v241
	v_max_f32_e32 v246, 0, v254
	v_max_f32_e32 v247, 0, v255
	v_max_f32_e32 v248, 0, v148
	v_max_f32_e32 v249, 0, v149
	v_fma_f32 v238, -|v254|, v238, v246
	v_fma_f32 v239, -|v255|, v239, v247
	v_fma_f32 v240, -|v148|, v240, v248
	v_fma_f32 v241, -|v149|, v241, v249
	v_pk_fma_f32 v[254:255], v[128:129], v[76:77], v[144:145]
	v_pk_fma_f32 v[148:149], v[130:131], v[78:79], v[146:147]
	v_fmac_f32_dpp v254, v76, v198 row_shr:1 row_mask:0xf bank_mask:0xf
	v_fmac_f32_dpp v255, v77, v199 row_shr:1 row_mask:0xf bank_mask:0xf
	v_fmac_f32_dpp v148, v78, v200 row_shr:1 row_mask:0xf bank_mask:0xf
	v_fmac_f32_dpp v149, v79, v201 row_shr:1 row_mask:0xf bank_mask:0xf
	v_fmac_f32_dpp v254, v76, v182 row_shr:2 row_mask:0xf bank_mask:0xf
	v_fmac_f32_dpp v255, v77, v183 row_shr:2 row_mask:0xf bank_mask:0xf
	v_fmac_f32_dpp v148, v78, v184 row_shr:2 row_mask:0xf bank_mask:0xf
	v_fmac_f32_dpp v149, v79, v185 row_shr:2 row_mask:0xf bank_mask:0xf
	v_fmac_f32_dpp v254, v232, v198 row_ror:1 row_mask:0xf bank_mask:0x1
	v_fmac_f32_dpp v255, v233, v199 row_ror:1 row_mask:0xf bank_mask:0x1
	v_fmac_f32_dpp v148, v234, v200 row_ror:1 row_mask:0xf bank_mask:0x1
	v_fmac_f32_dpp v149, v235, v201 row_ror:1 row_mask:0xf bank_mask:0x1
	v_fmac_f32_dpp v254, v232, v182 row_ror:2 row_mask:0xf bank_mask:0x1
	v_fmac_f32_dpp v255, v233, v183 row_ror:2 row_mask:0xf bank_mask:0x1
	v_fmac_f32_dpp v148, v234, v184 row_ror:2 row_mask:0xf bank_mask:0x1
	v_fmac_f32_dpp v149, v235, v185 row_ror:2 row_mask:0xf bank_mask:0x1
	v_pk_mul_f32 v[254:255], v[238:239], v[254:255]
	v_pk_mul_f32 v[148:149], v[240:241], v[148:149]
	v_cvt_pk_bf16_f32 v244, v254, v255
	v_cvt_pk_bf16_f32 v245, v148, v149
	global_store_dwordx4 v151, v[242:245], s[46:47]
	v_pk_fma_f32 v[254:255], v[202:203], v[60:61], v[132:133]
	v_pk_fma_f32 v[148:149], v[204:205], v[62:63], v[134:135]
	v_fmac_f32_dpp v254, v60, v186 row_shr:1 row_mask:0xf bank_mask:0xf
	v_fmac_f32_dpp v255, v61, v187 row_shr:1 row_mask:0xf bank_mask:0xf
	v_fmac_f32_dpp v148, v62, v188 row_shr:1 row_mask:0xf bank_mask:0xf
	v_fmac_f32_dpp v149, v63, v189 row_shr:1 row_mask:0xf bank_mask:0xf
	v_fmac_f32_dpp v254, v60, v170 row_shr:2 row_mask:0xf bank_mask:0xf
	v_fmac_f32_dpp v255, v61, v171 row_shr:2 row_mask:0xf bank_mask:0xf
	v_fmac_f32_dpp v148, v62, v172 row_shr:2 row_mask:0xf bank_mask:0xf
	v_fmac_f32_dpp v149, v63, v173 row_shr:2 row_mask:0xf bank_mask:0xf
	v_fmac_f32_dpp v254, v116, v186 row_ror:1 row_mask:0xf bank_mask:0x1
	v_fmac_f32_dpp v255, v117, v187 row_ror:1 row_mask:0xf bank_mask:0x1
	v_fmac_f32_dpp v148, v118, v188 row_ror:1 row_mask:0xf bank_mask:0x1
	v_fmac_f32_dpp v149, v119, v189 row_ror:1 row_mask:0xf bank_mask:0x1
	v_fmac_f32_dpp v254, v116, v170 row_ror:2 row_mask:0xf bank_mask:0x1
	v_fmac_f32_dpp v255, v117, v171 row_ror:2 row_mask:0xf bank_mask:0x1
	v_fmac_f32_dpp v148, v118, v172 row_ror:2 row_mask:0xf bank_mask:0x1
	v_fmac_f32_dpp v149, v119, v173 row_ror:2 row_mask:0xf bank_mask:0x1
	v_fma_f32 v246, |v254|, s38, 1.0
	v_fma_f32 v247, |v255|, s38, 1.0
	v_fma_f32 v248, |v148|, s38, 1.0
	v_fma_f32 v249, |v149|, s38, 1.0
	v_mul_f32_e32 v250, v254, v254
	v_mul_f32_e32 v251, v255, v255
	v_mul_f32_e32 v252, v148, v148
	v_mul_f32_e32 v253, v149, v149
	v_rcp_f32_e32 v246, v246
	v_rcp_f32_e32 v247, v247
	v_rcp_f32_e32 v248, v248
	v_rcp_f32_e32 v249, v249
	v_mul_f32_e32 v250, s72, v250
	v_mul_f32_e32 v251, s72, v251
	v_mul_f32_e32 v252, s72, v252
	v_mul_f32_e32 v253, s72, v253
	v_exp_f32_e32 v250, v250
	v_exp_f32_e32 v251, v251
	v_exp_f32_e32 v252, v252
	v_exp_f32_e32 v253, v253
	v_fmamk_f32 v238, v246, 0x3f07dc22, v219
	v_fmamk_f32 v239, v247, 0x3f07dc22, v219
	v_fmamk_f32 v240, v248, 0x3f07dc22, v219
	v_fmamk_f32 v241, v249, 0x3f07dc22, v219
	v_fma_f32 v238, v246, v238, s66
	v_fma_f32 v239, v247, v239, s66
	v_fma_f32 v240, v248, v240, s66
	v_fma_f32 v241, v249, v241, s66
	v_fma_f32 v238, v246, v238, s68
	v_fma_f32 v239, v247, v239, s68
	v_fma_f32 v240, v248, v240, s68
	v_fma_f32 v241, v249, v241, s68
	v_fma_f32 v238, v246, v238, s70
	v_fma_f32 v239, v247, v239, s70
	v_fma_f32 v240, v248, v240, s70
	v_fma_f32 v241, v249, v241, s70
	v_mul_f32_e32 v238, v246, v238
	v_mul_f32_e32 v239, v247, v239
	v_mul_f32_e32 v240, v248, v240
	v_mul_f32_e32 v241, v249, v241
	v_mul_f32_e32 v238, v250, v238
;     __device__ __forceinline__ void operator()(const f32x4 (&acc)[2][2][4][2], const Unit& u, int wr, int wc, int fr, int fq) const {
;     ...
;                         if ((u.pm & 7) == 7 && ai == 1 && wr == 1 && fr >= 14) *(f32x4*)(ncp + (size_t)((u.pm >> 3) * 2 + (fr - 14)) * FF2 + oc) = v[3];
;                     }
; #pragma unroll
;                     for (int m = 0; m < 4; ++m) {
;                         f32x4 cv;
;                         if (!samp) {
;                             const f32x4 prev = m ? v[m - 1] : hv;
; #pragma unroll
;                             for (int e = 0; e < 4; ++e) {
;                                 const int vi = __float_as_int(v[m][e]), pi = __float_as_int(prev[e]);
;                                 const int o1 = __builtin_amdgcn_mov_dpp(pi, 0x121, 0xf, 0xf, false);
;                                 const int o2 = __builtin_amdgcn_mov_dpp(pi, 0x122, 0xf, 0xf, false);
;                                 const float p1 = __int_as_float(__builtin_amdgcn_update_dpp(o1, vi, 0x111, 0xf, 0xf, false));
;                                 const float p2 = __int_as_float(__builtin_amdgcn_update_dpp(o2, vi, 0x112, 0xf, 0xf, false));
;                                 cv[e] = cb[e] + cw0[e] * p2 + cw1[e] * p1 + cw2[e] * v[m][e];
;                             }
;                         } else {
;                             const int ns = rowb + 16 * m + fr - MP;
;                             f32x4 s0 = (f32x4){0.f, 0.f, 0.f, 0.f}, s1 = s0;
;                             if (ns < NS) {
;                                 s0 = *(const f32x4*)(state + (size_t)(ns * 2 + 0) * FF2 + oc); s1 = *(const f32x4*)(state + (size_t)(ns * 2 + 1) * FF2 + oc);
;                                 *(f32x4*)(ncs + (size_t)(ns * 2 + 0) * FF2 + oc) = s1; *(f32x4*)(ncs + (size_t)(ns * 2 + 1) * FF2 + oc) = v[m];
;                             }
;                             cv = cb + cw0 * s0 + cw1 * s1 + cw2 * v[m];
;                         }
;                         if (bj == 0) cg[m] = gelu4(cv);
;                         else {
;                             const f32x4 r = cg[m] * cv;
;                             v2u w; w.x = cvt_pk_bf16(r[0], r[1]); w.y = cvt_pk_bf16(r[2], r[3]);
;                             *(v2u*)(ACT + (size_t)(rowb + 16 * m + fr) * FF + 128 * u.pn + 32 * wc + 8 * fq + 4 * n) = w;
;                         }
	v_mul_f32_e32 v239, v251, v239
	v_mul_f32_e32 v240, v252, v240
	v_mul_f32_e32 v241, v253, v241
	v_max_f32_e32 v246, 0, v254
	v_max_f32_e32 v247, 0, v255
	v_max_f32_e32 v248, 0, v148
	v_max_f32_e32 v249, 0, v149
	v_fma_f32 v238, -|v254|, v238, v246
	v_fma_f32 v239, -|v255|, v239, v247
	v_fma_f32 v240, -|v148|, v240, v248
	v_fma_f32 v241, -|v149|, v241, v249
	v_pk_fma_f32 v[254:255], v[210:211], v[44:45], v[140:141]
	v_pk_fma_f32 v[148:149], v[212:213], v[46:47], v[142:143]
	v_fmac_f32_dpp v254, v44, v194 row_shr:1 row_mask:0xf bank_mask:0xf
	v_fmac_f32_dpp v255, v45, v195 row_shr:1 row_mask:0xf bank_mask:0xf
	v_fmac_f32_dpp v148, v46, v196 row_shr:1 row_mask:0xf bank_mask:0xf
	v_fmac_f32_dpp v149, v47, v197 row_shr:1 row_mask:0xf bank_mask:0xf
	v_fmac_f32_dpp v254, v44, v178 row_shr:2 row_mask:0xf bank_mask:0xf
	v_fmac_f32_dpp v255, v45, v179 row_shr:2 row_mask:0xf bank_mask:0xf
	v_fmac_f32_dpp v148, v46, v180 row_shr:2 row_mask:0xf bank_mask:0xf
	v_fmac_f32_dpp v149, v47, v181 row_shr:2 row_mask:0xf bank_mask:0xf
	v_fmac_f32_dpp v254, v100, v194 row_ror:1 row_mask:0xf bank_mask:0x1
	v_fmac_f32_dpp v255, v101, v195 row_ror:1 row_mask:0xf bank_mask:0x1
	v_fmac_f32_dpp v148, v102, v196 row_ror:1 row_mask:0xf bank_mask:0x1
	v_fmac_f32_dpp v149, v103, v197 row_ror:1 row_mask:0xf bank_mask:0x1
	v_fmac_f32_dpp v254, v100, v178 row_ror:2 row_mask:0xf bank_mask:0x1
	v_fmac_f32_dpp v255, v101, v179 row_ror:2 row_mask:0xf bank_mask:0x1
	v_fmac_f32_dpp v148, v102, v180 row_ror:2 row_mask:0xf bank_mask:0x1
	v_fmac_f32_dpp v149, v103, v181 row_ror:2 row_mask:0xf bank_mask:0x1
	v_pk_mul_f32 v[254:255], v[238:239], v[254:255]
	v_pk_mul_f32 v[148:149], v[240:241], v[148:149]
	v_cvt_pk_bf16_f32 v242, v254, v255
	v_cvt_pk_bf16_f32 v243, v148, v149
	v_pk_fma_f32 v[254:255], v[206:207], v[28:29], v[136:137]
	v_pk_fma_f32 v[148:149], v[208:209], v[30:31], v[138:139]
	v_fmac_f32_dpp v254, v28, v190 row_shr:1 row_mask:0xf bank_mask:0xf
	v_fmac_f32_dpp v255, v29, v191 row_shr:1 row_mask:0xf bank_mask:0xf
	v_fmac_f32_dpp v148, v30, v192 row_shr:1 row_mask:0xf bank_mask:0xf
	v_fmac_f32_dpp v149, v31, v193 row_shr:1 row_mask:0xf bank_mask:0xf
	v_fmac_f32_dpp v254, v28, v174 row_shr:2 row_mask:0xf bank_mask:0xf
	v_fmac_f32_dpp v255, v29, v175 row_shr:2 row_mask:0xf bank_mask:0xf
	v_fmac_f32_dpp v148, v30, v176 row_shr:2 row_mask:0xf bank_mask:0xf
	v_fmac_f32_dpp v149, v31, v177 row_shr:2 row_mask:0xf bank_mask:0xf
	v_fmac_f32_dpp v254, v84, v190 row_ror:1 row_mask:0xf bank_mask:0x1
	v_fmac_f32_dpp v255, v85, v191 row_ror:1 row_mask:0xf bank_mask:0x1
	v_fmac_f32_dpp v148, v86, v192 row_ror:1 row_mask:0xf bank_mask:0x1
	v_fmac_f32_dpp v149, v87, v193 row_ror:1 row_mask:0xf bank_mask:0x1
	v_fmac_f32_dpp v254, v84, v174 row_ror:2 row_mask:0xf bank_mask:0x1
	v_fmac_f32_dpp v255, v85, v175 row_ror:2 row_mask:0xf bank_mask:0x1
	v_fmac_f32_dpp v148, v86, v176 row_ror:2 row_mask:0xf bank_mask:0x1
	v_fmac_f32_dpp v149, v87, v177 row_ror:2 row_mask:0xf bank_mask:0x1
	v_fma_f32 v246, |v254|, s38, 1.0
	v_fma_f32 v247, |v255|, s38, 1.0
	v_fma_f32 v248, |v148|, s38, 1.0
	v_fma_f32 v249, |v149|, s38, 1.0
	v_mul_f32_e32 v250, v254, v254
	v_mul_f32_e32 v251, v255, v255
	v_mul_f32_e32 v252, v148, v148
	v_mul_f32_e32 v253, v149, v149
	v_rcp_f32_e32 v246, v246
	v_rcp_f32_e32 v247, v247
	v_rcp_f32_e32 v248, v248
	v_rcp_f32_e32 v249, v249
	v_mul_f32_e32 v250, s72, v250
	v_mul_f32_e32 v251, s72, v251
	v_mul_f32_e32 v252, s72, v252
	v_mul_f32_e32 v253, s72, v253
	v_exp_f32_e32 v250, v250
	v_exp_f32_e32 v251, v251
	v_exp_f32_e32 v252, v252
	v_exp_f32_e32 v253, v253
	v_fmamk_f32 v238, v246, 0x3f07dc22, v219
	v_fmamk_f32 v239, v247, 0x3f07dc22, v219
	v_fmamk_f32 v240, v248, 0x3f07dc22, v219
	v_fmamk_f32 v241, v249, 0x3f07dc22, v219
	v_fma_f32 v238, v246, v238, s66
	v_fma_f32 v239, v247, v239, s66
	v_fma_f32 v240, v248, v240, s66
	v_fma_f32 v241, v249, v241, s66
	v_fma_f32 v238, v246, v238, s68
	v_fma_f32 v239, v247, v239, s68
	v_fma_f32 v240, v248, v240, s68
	v_fma_f32 v241, v249, v241, s68
	v_fma_f32 v238, v246, v238, s70
	v_fma_f32 v239, v247, v239, s70
	v_fma_f32 v240, v248, v240, s70
	v_fma_f32 v241, v249, v241, s70
	v_mul_f32_e32 v238, v246, v238
	v_mul_f32_e32 v239, v247, v239
	v_mul_f32_e32 v240, v248, v240
	v_mul_f32_e32 v241, v249, v241
	v_mul_f32_e32 v238, v250, v238
	v_mul_f32_e32 v239, v251, v239
	v_mul_f32_e32 v240, v252, v240
	v_mul_f32_e32 v241, v253, v241
	v_max_f32_e32 v246, 0, v254
	v_max_f32_e32 v247, 0, v255
	v_max_f32_e32 v248, 0, v148
	v_max_f32_e32 v249, 0, v149
	v_fma_f32 v238, -|v254|, v238, v246
	v_fma_f32 v239, -|v255|, v239, v247
	v_fma_f32 v240, -|v148|, v240, v248
	v_fma_f32 v241, -|v149|, v241, v249
	v_pk_fma_f32 v[254:255], v[128:129], v[12:13], v[144:145]
	v_pk_fma_f32 v[148:149], v[130:131], v[14:15], v[146:147]
	v_fmac_f32_dpp v254, v12, v198 row_shr:1 row_mask:0xf bank_mask:0xf
	v_fmac_f32_dpp v255, v13, v199 row_shr:1 row_mask:0xf bank_mask:0xf
	v_fmac_f32_dpp v148, v14, v200 row_shr:1 row_mask:0xf bank_mask:0xf
	v_fmac_f32_dpp v149, v15, v201 row_shr:1 row_mask:0xf bank_mask:0xf
	v_fmac_f32_dpp v254, v12, v182 row_shr:2 row_mask:0xf bank_mask:0xf
	v_fmac_f32_dpp v255, v13, v183 row_shr:2 row_mask:0xf bank_mask:0xf
	v_fmac_f32_dpp v148, v14, v184 row_shr:2 row_mask:0xf bank_mask:0xf
	v_fmac_f32_dpp v149, v15, v185 row_shr:2 row_mask:0xf bank_mask:0xf
	v_fmac_f32_dpp v254, v68, v198 row_ror:1 row_mask:0xf bank_mask:0x1
	v_fmac_f32_dpp v255, v69, v199 row_ror:1 row_mask:0xf bank_mask:0x1
	v_fmac_f32_dpp v148, v70, v200 row_ror:1 row_mask:0xf bank_mask:0x1
	v_fmac_f32_dpp v149, v71, v201 row_ror:1 row_mask:0xf bank_mask:0x1
	v_fmac_f32_dpp v254, v68, v182 row_ror:2 row_mask:0xf bank_mask:0x1
	v_fmac_f32_dpp v255, v69, v183 row_ror:2 row_mask:0xf bank_mask:0x1
	v_fmac_f32_dpp v148, v70, v184 row_ror:2 row_mask:0xf bank_mask:0x1
	v_fmac_f32_dpp v149, v71, v185 row_ror:2 row_mask:0xf bank_mask:0x1
	v_pk_mul_f32 v[254:255], v[238:239], v[254:255]
	v_pk_mul_f32 v[148:149], v[240:241], v[148:149]
	v_cvt_pk_bf16_f32 v244, v254, v255
	v_cvt_pk_bf16_f32 v245, v148, v149
	s_add_u32 s56, s46, 0xb0000
	s_addc_u32 s57, s47, 0
	global_store_dwordx4 v151, v[242:245], s[56:57]
	s_and_b32 s14, s88, 7
	s_cmp_eq_u32 s14, 7
	s_cselect_b32 s14, s73, 0
	s_cmp_eq_u32 s14, 1
	s_cbranch_scc0 .Lfe_done
	s_lshr_b32 s14, s88, 3
	s_mul_i32 s14, s14, 0xb000
	v_mul_i32_i24_e32 v246, 0x5800, v216
	v_add_u32_e32 v246, s14, v246
	v_add_u32_e32 v246, v246, v237
	v_add_u32_e32 v247, 0x2c00, v246
	s_mov_b64 s[14:15], exec
	s_mov_b64 exec, s[10:11]
	global_store_dwordx4 v246, v[56:59], s[50:51]
	global_store_dwordx4 v246, v[24:27], s[50:51] offset:16
	global_store_dwordx4 v247, v[40:43], s[50:51]
	global_store_dwordx4 v247, v[8:11], s[50:51] offset:16
	s_mov_b64 exec, s[14:15]
